# sc8 + all K-loops: post-MFMA barrier issued 4 MFMAs before the block end, tail MFMAs at s_setprio 1
# speedup vs baseline: 1.0036x; 1.0036x over previous
.LBB0_256:
	v_add_u32_e32 v172, s70, v160
	v_add_u32_e32 v188, s71, v160
	ds_read_b128 v[154:157], v172
	ds_read_b128 v[164:167], v172 offset:1024
	ds_read_b128 v[168:171], v172 offset:2048
	ds_read_b128 v[172:175], v172 offset:3072
	ds_read_b128 v[176:179], v188
	ds_read_b128 v[180:183], v188 offset:1024
	ds_read_b128 v[184:187], v188 offset:2048
	ds_read_b128 v[188:191], v188 offset:3072
	s_add_i32 s75, s30, 2
	s_add_u32 s31, s28, 0xfffc0080
	s_addc_u32 s34, s29, -1
	s_cmp_eq_u32 s67, s30
	s_cselect_b32 s30, s26, s17
	s_cselect_b32 s35, s25, s34
	s_cselect_b32 s34, s24, s31
	s_cselect_b32 s31, s27, s19
	s_add_i32 m0, s58, 0xc000
	ds_read_b128 v[192:195], v163
	ds_read_b128 v[196:199], v163 offset:1024
	ds_read_b128 v[200:203], v163 offset:2048
	ds_read_b128 v[204:207], v163 offset:3072
	ds_read_b128 v[208:211], v163 offset:4096
	ds_read_b128 v[212:215], v163 offset:5120
	ds_read_b128 v[216:219], v163 offset:6144
	ds_read_b128 v[220:223], v163 offset:7168
	global_load_lds_dwordx4 v146, s[28:29]
	s_add_i32 m0, s58, 0xe000
	s_nop 0
	global_load_lds_dwordx4 v148, s[28:29]
	s_waitcnt vmcnt(8)
	s_waitcnt lgkmcnt(0)
	s_barrier
	v_mfma_f32_16x16x32_bf16 v[42:45], v[154:157], v[192:195], v[42:45]
	v_mfma_f32_16x16x32_bf16 v[42:45], v[164:167], v[196:199], v[42:45]
	v_mfma_f32_16x16x32_bf16 v[54:57], v[164:167], v[204:207], v[54:57]
	v_mfma_f32_16x16x32_bf16 v[54:57], v[154:157], v[200:203], v[54:57]
	v_mfma_f32_16x16x32_bf16 v[66:69], v[154:157], v[208:211], v[66:69]
	v_mfma_f32_16x16x32_bf16 v[66:69], v[164:167], v[212:215], v[66:69]
	v_mfma_f32_16x16x32_bf16 v[62:65], v[164:167], v[220:223], v[62:65]
	v_mfma_f32_16x16x32_bf16 v[62:65], v[154:157], v[216:219], v[62:65]
	v_mfma_f32_16x16x32_bf16 v[46:49], v[168:171], v[216:219], v[46:49]
	v_mfma_f32_16x16x32_bf16 v[46:49], v[172:175], v[220:223], v[46:49]
	v_mfma_f32_16x16x32_bf16 v[50:53], v[172:175], v[212:215], v[50:53]
	v_mfma_f32_16x16x32_bf16 v[50:53], v[168:171], v[208:211], v[50:53]
	v_mfma_f32_16x16x32_bf16 v[38:41], v[168:171], v[200:203], v[38:41]
	v_mfma_f32_16x16x32_bf16 v[38:41], v[172:175], v[204:207], v[38:41]
	v_mfma_f32_16x16x32_bf16 v[26:29], v[172:175], v[196:199], v[26:29]
	v_mfma_f32_16x16x32_bf16 v[26:29], v[168:171], v[192:195], v[26:29]
	v_mfma_f32_16x16x32_bf16 v[14:17], v[176:179], v[192:195], v[14:17]
	v_mfma_f32_16x16x32_bf16 v[14:17], v[180:183], v[196:199], v[14:17]
	v_mfma_f32_16x16x32_bf16 v[22:25], v[180:183], v[204:207], v[22:25]
	v_mfma_f32_16x16x32_bf16 v[22:25], v[176:179], v[200:203], v[22:25]
	v_mfma_f32_16x16x32_bf16 v[30:33], v[176:179], v[208:211], v[30:33]
	v_mfma_f32_16x16x32_bf16 v[30:33], v[180:183], v[212:215], v[30:33]
	v_mfma_f32_16x16x32_bf16 v[34:37], v[180:183], v[220:223], v[34:37]
	v_mfma_f32_16x16x32_bf16 v[34:37], v[176:179], v[216:219], v[34:37]
	v_mfma_f32_16x16x32_bf16 v[18:21], v[184:187], v[216:219], v[18:21]
	v_mfma_f32_16x16x32_bf16 v[18:21], v[188:191], v[220:223], v[18:21]
	v_mfma_f32_16x16x32_bf16 v[10:13], v[188:191], v[212:215], v[10:13]
	v_mfma_f32_16x16x32_bf16 v[10:13], v[184:187], v[208:211], v[10:13]
	s_setprio 1
	s_barrier
	v_mfma_f32_16x16x32_bf16 v[6:9], v[184:187], v[200:203], v[6:9]
	v_mfma_f32_16x16x32_bf16 v[6:9], v[188:191], v[204:207], v[6:9]
	v_mfma_f32_16x16x32_bf16 v[2:5], v[188:191], v[196:199], v[2:5]
	v_mfma_f32_16x16x32_bf16 v[2:5], v[184:187], v[192:195], v[2:5]
	s_setprio 0
	s_add_i32 s50, s70, s54
	s_mov_b32 m0, s50
	ds_read_b128 v[192:195], v163 offset:16384
	ds_read_b128 v[196:199], v163 offset:17408
	ds_read_b128 v[200:203], v163 offset:18432
	ds_read_b128 v[204:207], v163 offset:19456
	ds_read_b128 v[208:211], v163 offset:20480
	ds_read_b128 v[212:215], v163 offset:21504
	ds_read_b128 v[216:219], v163 offset:22528
	ds_read_b128 v[220:223], v163 offset:23552
	global_load_lds_dwordx4 v134, s[30:31]
	s_add_i32 m0, s50, 0x2000
	s_add_u32 s76, s30, 0x40000
	v_lshl_add_u64 v[226:227], s[30:31], 0, v[130:131]
	s_addc_u32 s77, s31, 0
	s_add_i32 s50, s71, s54
	global_load_lds_dwordx4 v130, s[30:31]
	s_mov_b32 m0, s50
	v_lshl_add_u64 v[230:231], s[34:35], 0, v[132:133]
	global_load_lds_dwordx4 v134, s[76:77]
	s_add_i32 m0, s50, 0x2000
	s_nop 0
	global_load_lds_dwordx4 v130, s[76:77]
	v_lshl_add_u64 v[228:229], s[34:35], 0, v[136:137]
	s_mov_b32 m0, s58
	s_nop 0
	global_load_lds_dwordx4 v136, s[34:35]
	s_mov_b32 m0, s59
	s_nop 0
	global_load_lds_dwordx4 v132, s[34:35]
	s_waitcnt vmcnt(8)
	s_waitcnt lgkmcnt(0)
	s_barrier
	v_mfma_f32_16x16x32_bf16 v[110:113], v[154:157], v[192:195], v[110:113]
	v_mfma_f32_16x16x32_bf16 v[110:113], v[164:167], v[196:199], v[110:113]
	v_mfma_f32_16x16x32_bf16 v[106:109], v[164:167], v[204:207], v[106:109]
	v_mfma_f32_16x16x32_bf16 v[106:109], v[154:157], v[200:203], v[106:109]
	v_mfma_f32_16x16x32_bf16 v[118:121], v[154:157], v[208:211], v[118:121]
	v_mfma_f32_16x16x32_bf16 v[118:121], v[164:167], v[212:215], v[118:121]
	v_mfma_f32_16x16x32_bf16 v[126:129], v[164:167], v[220:223], v[126:129]
	v_mfma_f32_16x16x32_bf16 v[126:129], v[154:157], v[216:219], v[126:129]
	v_mfma_f32_16x16x32_bf16 v[102:105], v[168:171], v[216:219], v[102:105]
	v_mfma_f32_16x16x32_bf16 v[102:105], v[172:175], v[220:223], v[102:105]
	v_mfma_f32_16x16x32_bf16 v[94:97], v[172:175], v[212:215], v[94:97]
	v_mfma_f32_16x16x32_bf16 v[94:97], v[168:171], v[208:211], v[94:97]
	v_mfma_f32_16x16x32_bf16 v[82:85], v[168:171], v[200:203], v[82:85]
	v_mfma_f32_16x16x32_bf16 v[82:85], v[172:175], v[204:207], v[82:85]
	v_mfma_f32_16x16x32_bf16 v[86:89], v[172:175], v[196:199], v[86:89]
	v_mfma_f32_16x16x32_bf16 v[86:89], v[168:171], v[192:195], v[86:89]
	v_mfma_f32_16x16x32_bf16 v[70:73], v[176:179], v[192:195], v[70:73]
	v_mfma_f32_16x16x32_bf16 v[70:73], v[180:183], v[196:199], v[70:73]
	v_mfma_f32_16x16x32_bf16 v[74:77], v[180:183], v[204:207], v[74:77]
	v_mfma_f32_16x16x32_bf16 v[74:77], v[176:179], v[200:203], v[74:77]
	v_mfma_f32_16x16x32_bf16 v[114:117], v[176:179], v[208:211], v[114:117]
	v_mfma_f32_16x16x32_bf16 v[114:117], v[180:183], v[212:215], v[114:117]
	v_mfma_f32_16x16x32_bf16 v[122:125], v[180:183], v[220:223], v[122:125]
	v_mfma_f32_16x16x32_bf16 v[122:125], v[176:179], v[216:219], v[122:125]
	v_mfma_f32_16x16x32_bf16 v[98:101], v[184:187], v[216:219], v[98:101]
	v_mfma_f32_16x16x32_bf16 v[98:101], v[188:191], v[220:223], v[98:101]
	v_mfma_f32_16x16x32_bf16 v[90:93], v[188:191], v[212:215], v[90:93]
	v_mfma_f32_16x16x32_bf16 v[90:93], v[184:187], v[208:211], v[90:93]
	s_setprio 1
	s_barrier
	v_mfma_f32_16x16x32_bf16 v[78:81], v[184:187], v[200:203], v[78:81]
	v_mfma_f32_16x16x32_bf16 v[78:81], v[188:191], v[204:207], v[78:81]
	v_mfma_f32_16x16x32_bf16 v[58:61], v[188:191], v[196:199], v[58:61]
	v_mfma_f32_16x16x32_bf16 v[58:61], v[184:187], v[192:195], v[58:61]
	s_setprio 0
	s_add_i32 s50, 0, 0x18000
	s_add_i32 s51, 0, 0x1c000
	v_add_u32_e32 v172, s50, v160
	v_add_u32_e32 v188, s51, v160
	ds_read_b128 v[154:157], v172
	ds_read_b128 v[164:167], v172 offset:1024
	ds_read_b128 v[168:171], v172 offset:2048
	ds_read_b128 v[172:175], v172 offset:3072
	ds_read_b128 v[176:179], v188
	ds_read_b128 v[180:183], v188 offset:1024
	ds_read_b128 v[184:187], v188 offset:2048
	ds_read_b128 v[188:191], v188 offset:3072
	s_add_u32 s34, s34, 0x40000
	s_addc_u32 s35, s35, 0
	s_mov_b32 m0, s60
	ds_read_b128 v[192:195], v163 offset:32768
	ds_read_b128 v[196:199], v163 offset:33792
	ds_read_b128 v[200:203], v163 offset:34816
	ds_read_b128 v[204:207], v163 offset:35840
	ds_read_b128 v[208:211], v163 offset:36864
	ds_read_b128 v[212:215], v163 offset:37888
	ds_read_b128 v[216:219], v163 offset:38912
	ds_read_b128 v[220:223], v163 offset:39936
	global_load_lds_dwordx4 v136, s[34:35]
	s_mov_b32 m0, s61
	s_nop 0
	global_load_lds_dwordx4 v132, s[34:35]
	s_waitcnt vmcnt(8)
	s_waitcnt lgkmcnt(0)
	s_barrier
	v_mfma_f32_16x16x32_bf16 v[42:45], v[154:157], v[192:195], v[42:45]
	v_mfma_f32_16x16x32_bf16 v[42:45], v[164:167], v[196:199], v[42:45]
	v_mfma_f32_16x16x32_bf16 v[54:57], v[164:167], v[204:207], v[54:57]
	v_mfma_f32_16x16x32_bf16 v[54:57], v[154:157], v[200:203], v[54:57]
	v_mfma_f32_16x16x32_bf16 v[66:69], v[154:157], v[208:211], v[66:69]
	v_mfma_f32_16x16x32_bf16 v[66:69], v[164:167], v[212:215], v[66:69]
	v_mfma_f32_16x16x32_bf16 v[62:65], v[164:167], v[220:223], v[62:65]
	v_mfma_f32_16x16x32_bf16 v[62:65], v[154:157], v[216:219], v[62:65]
	v_mfma_f32_16x16x32_bf16 v[46:49], v[168:171], v[216:219], v[46:49]
	v_mfma_f32_16x16x32_bf16 v[46:49], v[172:175], v[220:223], v[46:49]
	v_mfma_f32_16x16x32_bf16 v[50:53], v[172:175], v[212:215], v[50:53]
	v_mfma_f32_16x16x32_bf16 v[50:53], v[168:171], v[208:211], v[50:53]
	v_mfma_f32_16x16x32_bf16 v[38:41], v[168:171], v[200:203], v[38:41]
	v_mfma_f32_16x16x32_bf16 v[38:41], v[172:175], v[204:207], v[38:41]
	v_mfma_f32_16x16x32_bf16 v[26:29], v[172:175], v[196:199], v[26:29]
	v_mfma_f32_16x16x32_bf16 v[26:29], v[168:171], v[192:195], v[26:29]
	v_mfma_f32_16x16x32_bf16 v[14:17], v[176:179], v[192:195], v[14:17]
	v_mfma_f32_16x16x32_bf16 v[14:17], v[180:183], v[196:199], v[14:17]
	v_mfma_f32_16x16x32_bf16 v[22:25], v[180:183], v[204:207], v[22:25]
	v_mfma_f32_16x16x32_bf16 v[22:25], v[176:179], v[200:203], v[22:25]
	v_mfma_f32_16x16x32_bf16 v[30:33], v[176:179], v[208:211], v[30:33]
	v_mfma_f32_16x16x32_bf16 v[30:33], v[180:183], v[212:215], v[30:33]
	v_mfma_f32_16x16x32_bf16 v[34:37], v[180:183], v[220:223], v[34:37]
	v_mfma_f32_16x16x32_bf16 v[34:37], v[176:179], v[216:219], v[34:37]
	v_mfma_f32_16x16x32_bf16 v[18:21], v[184:187], v[216:219], v[18:21]
	v_mfma_f32_16x16x32_bf16 v[18:21], v[188:191], v[220:223], v[18:21]
	v_mfma_f32_16x16x32_bf16 v[10:13], v[188:191], v[212:215], v[10:13]
	v_mfma_f32_16x16x32_bf16 v[10:13], v[184:187], v[208:211], v[10:13]
	s_setprio 1
	s_barrier
	v_mfma_f32_16x16x32_bf16 v[6:9], v[184:187], v[200:203], v[6:9]
	v_mfma_f32_16x16x32_bf16 v[6:9], v[188:191], v[204:207], v[6:9]
	v_mfma_f32_16x16x32_bf16 v[2:5], v[188:191], v[196:199], v[2:5]
	v_mfma_f32_16x16x32_bf16 v[2:5], v[184:187], v[192:195], v[2:5]
	s_setprio 0
	s_add_i32 s34, s50, s54
	s_mov_b32 m0, s34
	ds_read_b128 v[192:195], v163 offset:49152
	ds_read_b128 v[196:199], v163 offset:50176
	ds_read_b128 v[200:203], v163 offset:51200
	ds_read_b128 v[204:207], v163 offset:52224
	ds_read_b128 v[208:211], v163 offset:53248
	ds_read_b128 v[212:215], v163 offset:54272
	ds_read_b128 v[216:219], v163 offset:55296
	ds_read_b128 v[220:223], v163 offset:56320
	s_add_u32 s98, s30, s10
	s_addc_u32 s99, s31, s11
	global_load_lds_dwordx4 v134, s[98:99]
	s_add_i32 m0, s34, 0x2000
	s_add_u32 s30, s30, 0x40080
	v_lshl_add_u64 v[224:225], v[226:227], 0, s[10:11]
	s_addc_u32 s31, s31, 0
	s_add_i32 s34, s51, s54
	global_load_lds_dwordx4 v[224:225], off
	s_mov_b32 m0, s34
	s_nop 0
	global_load_lds_dwordx4 v134, s[30:31]
	s_add_i32 m0, s34, 0x2000
	s_nop 0
	global_load_lds_dwordx4 v130, s[30:31]
	v_lshl_add_u64 v[224:225], v[228:229], 0, s[10:11]
	s_mov_b32 m0, s65
	s_nop 0
	global_load_lds_dwordx4 v[224:225], off
	v_lshl_add_u64 v[224:225], v[230:231], 0, s[10:11]
	s_mov_b32 m0, s66
	s_nop 0
	global_load_lds_dwordx4 v[224:225], off
	s_waitcnt vmcnt(8)
	s_waitcnt lgkmcnt(0)
	s_barrier
	v_mfma_f32_16x16x32_bf16 v[110:113], v[154:157], v[192:195], v[110:113]
	v_mfma_f32_16x16x32_bf16 v[110:113], v[164:167], v[196:199], v[110:113]
	v_mfma_f32_16x16x32_bf16 v[106:109], v[164:167], v[204:207], v[106:109]
	v_mfma_f32_16x16x32_bf16 v[106:109], v[154:157], v[200:203], v[106:109]
	v_mfma_f32_16x16x32_bf16 v[118:121], v[154:157], v[208:211], v[118:121]
	v_mfma_f32_16x16x32_bf16 v[118:121], v[164:167], v[212:215], v[118:121]
	v_mfma_f32_16x16x32_bf16 v[126:129], v[164:167], v[220:223], v[126:129]
	v_mfma_f32_16x16x32_bf16 v[126:129], v[154:157], v[216:219], v[126:129]
	v_mfma_f32_16x16x32_bf16 v[102:105], v[168:171], v[216:219], v[102:105]
	v_mfma_f32_16x16x32_bf16 v[102:105], v[172:175], v[220:223], v[102:105]
	v_mfma_f32_16x16x32_bf16 v[94:97], v[172:175], v[212:215], v[94:97]
	v_mfma_f32_16x16x32_bf16 v[94:97], v[168:171], v[208:211], v[94:97]
	v_mfma_f32_16x16x32_bf16 v[82:85], v[168:171], v[200:203], v[82:85]
	v_mfma_f32_16x16x32_bf16 v[82:85], v[172:175], v[204:207], v[82:85]
	v_mfma_f32_16x16x32_bf16 v[86:89], v[172:175], v[196:199], v[86:89]
	v_mfma_f32_16x16x32_bf16 v[86:89], v[168:171], v[192:195], v[86:89]
	v_mfma_f32_16x16x32_bf16 v[70:73], v[176:179], v[192:195], v[70:73]
	v_mfma_f32_16x16x32_bf16 v[70:73], v[180:183], v[196:199], v[70:73]
	v_mfma_f32_16x16x32_bf16 v[74:77], v[180:183], v[204:207], v[74:77]
	v_mfma_f32_16x16x32_bf16 v[74:77], v[176:179], v[200:203], v[74:77]
	v_mfma_f32_16x16x32_bf16 v[114:117], v[176:179], v[208:211], v[114:117]
	v_mfma_f32_16x16x32_bf16 v[114:117], v[180:183], v[212:215], v[114:117]
	v_mfma_f32_16x16x32_bf16 v[122:125], v[180:183], v[220:223], v[122:125]
	v_mfma_f32_16x16x32_bf16 v[122:125], v[176:179], v[216:219], v[122:125]
	v_mfma_f32_16x16x32_bf16 v[98:101], v[184:187], v[216:219], v[98:101]
	v_mfma_f32_16x16x32_bf16 v[98:101], v[188:191], v[220:223], v[98:101]
	v_mfma_f32_16x16x32_bf16 v[90:93], v[188:191], v[212:215], v[90:93]
	v_mfma_f32_16x16x32_bf16 v[90:93], v[184:187], v[208:211], v[90:93]
	s_setprio 1
	s_barrier
	v_mfma_f32_16x16x32_bf16 v[78:81], v[184:187], v[200:203], v[78:81]
	v_mfma_f32_16x16x32_bf16 v[78:81], v[188:191], v[204:207], v[78:81]
	v_mfma_f32_16x16x32_bf16 v[58:61], v[188:191], v[196:199], v[58:61]
	v_mfma_f32_16x16x32_bf16 v[58:61], v[184:187], v[192:195], v[58:61]
	s_setprio 0
	s_add_u32 s28, s28, 0x100
	s_addc_u32 s29, s29, 0
	s_add_u32 s17, s17, 0x100
	s_addc_u32 s19, s19, 0
	s_cmp_ge_i32 s75, s62
	s_mov_b32 s30, s75
	s_cbranch_scc0 .LBB0_256

.LBB0_351:
	v_add_u32_e32 v81, s62, v78
	s_waitcnt lgkmcnt(0)
	ds_read_b128 v[82:85], v81
	ds_read_b128 v[86:89], v81 offset:1024
	ds_read_b128 v[90:93], v81 offset:2048
	ds_read_b128 v[94:97], v81 offset:3072
	s_add_i32 s72, s24, 2
	s_add_u32 s22, s20, 0x100
	s_addc_u32 s23, s21, 0
	s_cmp_eq_u32 s61, s24
	s_cselect_b32 s24, s16, s70
	s_cselect_b32 s27, s15, s23
	s_cselect_b32 s26, s14, s22
	s_cselect_b32 s25, s17, s71
	s_mov_b32 m0, s63
	ds_read_b128 v[98:101], v79
	ds_read_b128 v[102:105], v79 offset:1024
	ds_read_b128 v[106:109], v79 offset:2048
	ds_read_b128 v[110:113], v79 offset:3072
	ds_read_b128 v[114:117], v79 offset:4096
	ds_read_b128 v[118:121], v79 offset:5120
	ds_read_b128 v[122:125], v79 offset:6144
	ds_read_b128 v[126:129], v79 offset:7168
	global_load_lds_dwordx4 v74, s[20:21]
	s_mov_b32 m0, s64
	s_nop 0
	global_load_lds_dwordx4 v76, s[20:21]
	s_waitcnt vmcnt(8)
	s_waitcnt lgkmcnt(0)
	s_barrier
	v_mfma_f32_16x16x32_bf16 v[62:65], v[82:85], v[98:101], v[62:65]
	v_mfma_f32_16x16x32_bf16 v[62:65], v[86:89], v[102:105], v[62:65]
	v_mfma_f32_16x16x32_bf16 v[54:57], v[86:89], v[110:113], v[54:57]
	v_mfma_f32_16x16x32_bf16 v[54:57], v[82:85], v[106:109], v[54:57]
	v_mfma_f32_16x16x32_bf16 v[46:49], v[82:85], v[114:117], v[46:49]
	v_mfma_f32_16x16x32_bf16 v[46:49], v[86:89], v[118:121], v[46:49]
	v_mfma_f32_16x16x32_bf16 v[34:37], v[86:89], v[126:129], v[34:37]
	v_mfma_f32_16x16x32_bf16 v[34:37], v[82:85], v[122:125], v[34:37]
	v_mfma_f32_16x16x32_bf16 v[26:29], v[90:93], v[122:125], v[26:29]
	v_mfma_f32_16x16x32_bf16 v[26:29], v[94:97], v[126:129], v[26:29]
	v_mfma_f32_16x16x32_bf16 v[42:45], v[94:97], v[118:121], v[42:45]
	v_mfma_f32_16x16x32_bf16 v[42:45], v[90:93], v[114:117], v[42:45]
	s_setprio 1
	s_barrier
	v_mfma_f32_16x16x32_bf16 v[50:53], v[90:93], v[106:109], v[50:53]
	v_mfma_f32_16x16x32_bf16 v[50:53], v[94:97], v[110:113], v[50:53]
	v_mfma_f32_16x16x32_bf16 v[58:61], v[94:97], v[102:105], v[58:61]
	v_mfma_f32_16x16x32_bf16 v[58:61], v[90:93], v[98:101], v[58:61]
	s_setprio 0
	s_mov_b32 m0, s65
	s_add_u32 s20, s24, 0x10000
	ds_read_b128 v[98:101], v79 offset:16384
	ds_read_b128 v[102:105], v79 offset:17408
	ds_read_b128 v[106:109], v79 offset:18432
	ds_read_b128 v[110:113], v79 offset:19456
	ds_read_b128 v[114:117], v79 offset:20480
	ds_read_b128 v[118:121], v79 offset:21504
	ds_read_b128 v[122:125], v79 offset:22528
	ds_read_b128 v[126:129], v79 offset:23552
	global_load_lds_dwordx4 v70, s[24:25]
	s_mov_b32 m0, s66
	s_addc_u32 s21, s25, 0
	global_load_lds_dwordx4 v66, s[24:25]
	s_mov_b32 m0, s34
	global_load_lds_dwordx4 v70, s[20:21]
	s_mov_b32 m0, s35
	s_nop 0
	global_load_lds_dwordx4 v66, s[20:21]
	s_mov_b32 m0, s31
	s_nop 0
	global_load_lds_dwordx4 v72, s[26:27]
	s_mov_b32 m0, s52
	s_nop 0
	global_load_lds_dwordx4 v68, s[26:27]
	s_waitcnt vmcnt(8)
	s_waitcnt lgkmcnt(0)
	s_barrier
	v_mfma_f32_16x16x32_bf16 v[38:41], v[82:85], v[98:101], v[38:41]
	v_mfma_f32_16x16x32_bf16 v[38:41], v[86:89], v[102:105], v[38:41]
	v_mfma_f32_16x16x32_bf16 v[22:25], v[86:89], v[110:113], v[22:25]
	v_mfma_f32_16x16x32_bf16 v[22:25], v[82:85], v[106:109], v[22:25]
	v_mfma_f32_16x16x32_bf16 v[14:17], v[82:85], v[114:117], v[14:17]
	v_mfma_f32_16x16x32_bf16 v[14:17], v[86:89], v[118:121], v[14:17]
	v_mfma_f32_16x16x32_bf16 v[6:9], v[86:89], v[126:129], v[6:9]
	v_mfma_f32_16x16x32_bf16 v[6:9], v[82:85], v[122:125], v[6:9]
	v_mfma_f32_16x16x32_bf16 v[2:5], v[90:93], v[122:125], v[2:5]
	v_mfma_f32_16x16x32_bf16 v[2:5], v[94:97], v[126:129], v[2:5]
	v_mfma_f32_16x16x32_bf16 v[10:13], v[94:97], v[118:121], v[10:13]
	v_mfma_f32_16x16x32_bf16 v[10:13], v[90:93], v[114:117], v[10:13]
	s_setprio 1
	s_barrier
	v_mfma_f32_16x16x32_bf16 v[18:21], v[90:93], v[106:109], v[18:21]
	v_mfma_f32_16x16x32_bf16 v[18:21], v[94:97], v[110:113], v[18:21]
	v_mfma_f32_16x16x32_bf16 v[30:33], v[94:97], v[102:105], v[30:33]
	v_mfma_f32_16x16x32_bf16 v[30:33], v[90:93], v[98:101], v[30:33]
	s_setprio 0
	v_add_u32_e32 v81, s67, v78
	ds_read_b128 v[82:85], v81
	ds_read_b128 v[86:89], v81 offset:1024
	ds_read_b128 v[90:93], v81 offset:2048
	ds_read_b128 v[94:97], v81 offset:3072
	s_add_u32 s20, s26, 0x18000
	s_addc_u32 s21, s27, 0
	s_mov_b32 m0, s53
	ds_read_b128 v[98:101], v79 offset:32768
	ds_read_b128 v[102:105], v79 offset:33792
	ds_read_b128 v[106:109], v79 offset:34816
	ds_read_b128 v[110:113], v79 offset:35840
	ds_read_b128 v[114:117], v79 offset:36864
	ds_read_b128 v[118:121], v79 offset:37888
	ds_read_b128 v[122:125], v79 offset:38912
	ds_read_b128 v[126:129], v79 offset:39936
	global_load_lds_dwordx4 v72, s[20:21]
	s_mov_b32 m0, s54
	s_nop 0
	global_load_lds_dwordx4 v68, s[20:21]
	s_waitcnt vmcnt(8)
	s_waitcnt lgkmcnt(0)
	s_barrier
	v_mfma_f32_16x16x32_bf16 v[62:65], v[82:85], v[98:101], v[62:65]
	v_mfma_f32_16x16x32_bf16 v[62:65], v[86:89], v[102:105], v[62:65]
	v_mfma_f32_16x16x32_bf16 v[54:57], v[86:89], v[110:113], v[54:57]
	v_mfma_f32_16x16x32_bf16 v[54:57], v[82:85], v[106:109], v[54:57]
	v_mfma_f32_16x16x32_bf16 v[46:49], v[82:85], v[114:117], v[46:49]
	v_mfma_f32_16x16x32_bf16 v[46:49], v[86:89], v[118:121], v[46:49]
	v_mfma_f32_16x16x32_bf16 v[34:37], v[86:89], v[126:129], v[34:37]
	v_mfma_f32_16x16x32_bf16 v[34:37], v[82:85], v[122:125], v[34:37]
	v_mfma_f32_16x16x32_bf16 v[26:29], v[90:93], v[122:125], v[26:29]
	v_mfma_f32_16x16x32_bf16 v[26:29], v[94:97], v[126:129], v[26:29]
	v_mfma_f32_16x16x32_bf16 v[42:45], v[94:97], v[118:121], v[42:45]
	v_mfma_f32_16x16x32_bf16 v[42:45], v[90:93], v[114:117], v[42:45]
	s_setprio 1
	s_barrier
	v_mfma_f32_16x16x32_bf16 v[50:53], v[90:93], v[106:109], v[50:53]
	v_mfma_f32_16x16x32_bf16 v[50:53], v[94:97], v[110:113], v[50:53]
	v_mfma_f32_16x16x32_bf16 v[58:61], v[94:97], v[102:105], v[58:61]
	v_mfma_f32_16x16x32_bf16 v[58:61], v[90:93], v[98:101], v[58:61]
	s_setprio 0
	s_mov_b32 m0, s68
	s_add_u32 s20, s24, 0x10080
	ds_read_b128 v[98:101], v79 offset:49152
	ds_read_b128 v[102:105], v79 offset:50176
	ds_read_b128 v[106:109], v79 offset:51200
	ds_read_b128 v[110:113], v79 offset:52224
	ds_read_b128 v[114:117], v79 offset:53248
	ds_read_b128 v[118:121], v79 offset:54272
	ds_read_b128 v[122:125], v79 offset:55296
	ds_read_b128 v[126:129], v79 offset:56320
	s_add_u32 s98, s24, s6
	s_addc_u32 s99, s25, s7
	global_load_lds_dwordx4 v70, s[98:99]
	s_mov_b32 m0, s69
	s_addc_u32 s21, s25, 0
	s_add_u32 s100, s24, s6
	s_addc_u32 s101, s25, s7
	global_load_lds_dwordx4 v66, s[100:101]
	s_mov_b32 m0, s59
	s_nop 0
	global_load_lds_dwordx4 v70, s[20:21]
	s_mov_b32 m0, s60
	s_nop 0
	global_load_lds_dwordx4 v66, s[20:21]
	s_mov_b32 m0, s57
	s_nop 0
	s_add_u32 s98, s26, s6
	s_addc_u32 s99, s27, s7
	global_load_lds_dwordx4 v72, s[98:99]
	s_mov_b32 m0, s58
	s_nop 0
	s_add_u32 s100, s26, s6
	s_addc_u32 s101, s27, s7
	global_load_lds_dwordx4 v68, s[100:101]
	s_waitcnt vmcnt(8)
	s_waitcnt lgkmcnt(0)
	s_barrier
	v_mfma_f32_16x16x32_bf16 v[38:41], v[82:85], v[98:101], v[38:41]
	v_mfma_f32_16x16x32_bf16 v[38:41], v[86:89], v[102:105], v[38:41]
	v_mfma_f32_16x16x32_bf16 v[22:25], v[86:89], v[110:113], v[22:25]
	v_mfma_f32_16x16x32_bf16 v[22:25], v[82:85], v[106:109], v[22:25]
	v_mfma_f32_16x16x32_bf16 v[14:17], v[82:85], v[114:117], v[14:17]
	v_mfma_f32_16x16x32_bf16 v[14:17], v[86:89], v[118:121], v[14:17]
	v_mfma_f32_16x16x32_bf16 v[6:9], v[86:89], v[126:129], v[6:9]
	v_mfma_f32_16x16x32_bf16 v[6:9], v[82:85], v[122:125], v[6:9]
	v_mfma_f32_16x16x32_bf16 v[2:5], v[90:93], v[122:125], v[2:5]
	v_mfma_f32_16x16x32_bf16 v[2:5], v[94:97], v[126:129], v[2:5]
	v_mfma_f32_16x16x32_bf16 v[10:13], v[94:97], v[118:121], v[10:13]
	v_mfma_f32_16x16x32_bf16 v[10:13], v[90:93], v[114:117], v[10:13]
	s_setprio 1
	s_barrier
	v_mfma_f32_16x16x32_bf16 v[18:21], v[90:93], v[106:109], v[18:21]
	v_mfma_f32_16x16x32_bf16 v[18:21], v[94:97], v[110:113], v[18:21]
	v_mfma_f32_16x16x32_bf16 v[30:33], v[94:97], v[102:105], v[30:33]
	v_mfma_f32_16x16x32_bf16 v[30:33], v[90:93], v[98:101], v[30:33]
	s_setprio 0
	s_add_u32 s70, s70, 0x100
	s_addc_u32 s71, s71, 0
	s_cmp_ge_i32 s72, s56
	s_mov_b64 s[20:21], s[22:23]
	s_mov_b32 s24, s72
	s_cbranch_scc0 .LBB0_351

.LBB0_468:
	v_add_u32_e32 v144, s62, v1
	ds_read_b128 v[150:153], v144
	ds_read_b128 v[154:157], v144 offset:1024
	ds_read_b128 v[158:161], v144 offset:2048
	ds_read_b128 v[162:165], v144 offset:3072
	v_add_u32_e32 v144, s63, v1
	ds_read_b128 v[166:169], v144
	ds_read_b128 v[170:173], v144 offset:1024
	ds_read_b128 v[174:177], v144 offset:2048
	ds_read_b128 v[178:181], v144 offset:3072
	s_add_i32 s77, s26, 2
	s_add_u32 s24, s22, 0x100
	s_addc_u32 s25, s23, 0
	s_cmp_eq_u32 s61, s26
	s_cselect_b32 s26, s16, s75
	s_cselect_b32 s29, s15, s25
	s_cselect_b32 s28, s14, s24
	s_cselect_b32 s27, s17, s76
	s_mov_b32 m0, s64
	ds_read_b128 v[182:185], v149
	ds_read_b128 v[186:189], v149 offset:1024
	ds_read_b128 v[190:193], v149 offset:2048
	ds_read_b128 v[194:197], v149 offset:3072
	ds_read_b128 v[198:201], v149 offset:4096
	ds_read_b128 v[202:205], v149 offset:5120
	ds_read_b128 v[206:209], v149 offset:6144
	ds_read_b128 v[210:213], v149 offset:7168
	global_load_lds_dwordx4 v140, s[22:23]
	s_mov_b32 m0, s65
	s_nop 0
	global_load_lds_dwordx4 v142, s[22:23]
	s_waitcnt vmcnt(8)
	s_waitcnt lgkmcnt(0)
	s_barrier
	v_mfma_f32_16x16x32_bf16 v[126:129], v[150:153], v[182:185], v[126:129]
	v_mfma_f32_16x16x32_bf16 v[126:129], v[154:157], v[186:189], v[126:129]
	v_mfma_f32_16x16x32_bf16 v[110:113], v[154:157], v[194:197], v[110:113]
	v_mfma_f32_16x16x32_bf16 v[110:113], v[150:153], v[190:193], v[110:113]
	v_mfma_f32_16x16x32_bf16 v[94:97], v[150:153], v[198:201], v[94:97]
	v_mfma_f32_16x16x32_bf16 v[94:97], v[154:157], v[202:205], v[94:97]
	v_mfma_f32_16x16x32_bf16 v[78:81], v[154:157], v[210:213], v[78:81]
	v_mfma_f32_16x16x32_bf16 v[78:81], v[150:153], v[206:209], v[78:81]
	v_mfma_f32_16x16x32_bf16 v[74:77], v[158:161], v[206:209], v[74:77]
	v_mfma_f32_16x16x32_bf16 v[74:77], v[162:165], v[210:213], v[74:77]
	v_mfma_f32_16x16x32_bf16 v[90:93], v[162:165], v[202:205], v[90:93]
	v_mfma_f32_16x16x32_bf16 v[90:93], v[158:161], v[198:201], v[90:93]
	v_mfma_f32_16x16x32_bf16 v[106:109], v[158:161], v[190:193], v[106:109]
	v_mfma_f32_16x16x32_bf16 v[106:109], v[162:165], v[194:197], v[106:109]
	v_mfma_f32_16x16x32_bf16 v[122:125], v[162:165], v[186:189], v[122:125]
	v_mfma_f32_16x16x32_bf16 v[122:125], v[158:161], v[182:185], v[122:125]
	v_mfma_f32_16x16x32_bf16 v[118:121], v[166:169], v[182:185], v[118:121]
	v_mfma_f32_16x16x32_bf16 v[118:121], v[170:173], v[186:189], v[118:121]
	v_mfma_f32_16x16x32_bf16 v[102:105], v[170:173], v[194:197], v[102:105]
	v_mfma_f32_16x16x32_bf16 v[102:105], v[166:169], v[190:193], v[102:105]
	v_mfma_f32_16x16x32_bf16 v[86:89], v[166:169], v[198:201], v[86:89]
	v_mfma_f32_16x16x32_bf16 v[86:89], v[170:173], v[202:205], v[86:89]
	v_mfma_f32_16x16x32_bf16 v[70:73], v[170:173], v[210:213], v[70:73]
	v_mfma_f32_16x16x32_bf16 v[70:73], v[166:169], v[206:209], v[70:73]
	v_mfma_f32_16x16x32_bf16 v[66:69], v[174:177], v[206:209], v[66:69]
	v_mfma_f32_16x16x32_bf16 v[66:69], v[178:181], v[210:213], v[66:69]
	v_mfma_f32_16x16x32_bf16 v[82:85], v[178:181], v[202:205], v[82:85]
	v_mfma_f32_16x16x32_bf16 v[82:85], v[174:177], v[198:201], v[82:85]
	s_setprio 1
	s_barrier
	v_mfma_f32_16x16x32_bf16 v[98:101], v[174:177], v[190:193], v[98:101]
	v_mfma_f32_16x16x32_bf16 v[98:101], v[178:181], v[194:197], v[98:101]
	v_mfma_f32_16x16x32_bf16 v[114:117], v[178:181], v[186:189], v[114:117]
	v_mfma_f32_16x16x32_bf16 v[114:117], v[174:177], v[182:185], v[114:117]
	s_setprio 0
	s_mov_b32 m0, s66
	s_add_u32 s22, s26, 0x18000
	ds_read_b128 v[182:185], v149 offset:16384
	ds_read_b128 v[186:189], v149 offset:17408
	ds_read_b128 v[190:193], v149 offset:18432
	ds_read_b128 v[194:197], v149 offset:19456
	ds_read_b128 v[198:201], v149 offset:20480
	ds_read_b128 v[202:205], v149 offset:21504
	ds_read_b128 v[206:209], v149 offset:22528
	ds_read_b128 v[210:213], v149 offset:23552
	global_load_lds_dwordx4 v134, s[26:27]
	v_lshl_add_u64 v[214:215], s[26:27], 0, v[130:131]
	s_mov_b32 m0, s67
	s_addc_u32 s23, s27, 0
	global_load_lds_dwordx4 v130, s[26:27]
	s_mov_b32 m0, s68
	global_load_lds_dwordx4 v134, s[22:23]
	s_mov_b32 m0, s69
	s_nop 0
	global_load_lds_dwordx4 v130, s[22:23]
	s_mov_b32 m0, s34
	s_nop 0
	global_load_lds_dwordx4 v136, s[28:29]
	s_mov_b32 m0, s35
	s_nop 0
	global_load_lds_dwordx4 v132, s[28:29]
	s_waitcnt vmcnt(8)
	s_waitcnt lgkmcnt(0)
	s_barrier
	v_mfma_f32_16x16x32_bf16 v[62:65], v[150:153], v[182:185], v[62:65]
	v_mfma_f32_16x16x32_bf16 v[62:65], v[154:157], v[186:189], v[62:65]
	v_mfma_f32_16x16x32_bf16 v[46:49], v[154:157], v[194:197], v[46:49]
	v_mfma_f32_16x16x32_bf16 v[46:49], v[150:153], v[190:193], v[46:49]
	v_mfma_f32_16x16x32_bf16 v[30:33], v[150:153], v[198:201], v[30:33]
	v_mfma_f32_16x16x32_bf16 v[30:33], v[154:157], v[202:205], v[30:33]
	v_mfma_f32_16x16x32_bf16 v[14:17], v[154:157], v[210:213], v[14:17]
	v_mfma_f32_16x16x32_bf16 v[14:17], v[150:153], v[206:209], v[14:17]
	v_mfma_f32_16x16x32_bf16 v[10:13], v[158:161], v[206:209], v[10:13]
	v_mfma_f32_16x16x32_bf16 v[10:13], v[162:165], v[210:213], v[10:13]
	v_mfma_f32_16x16x32_bf16 v[26:29], v[162:165], v[202:205], v[26:29]
	v_mfma_f32_16x16x32_bf16 v[26:29], v[158:161], v[198:201], v[26:29]
	v_mfma_f32_16x16x32_bf16 v[42:45], v[158:161], v[190:193], v[42:45]
	v_mfma_f32_16x16x32_bf16 v[42:45], v[162:165], v[194:197], v[42:45]
	v_mfma_f32_16x16x32_bf16 v[58:61], v[162:165], v[186:189], v[58:61]
	v_mfma_f32_16x16x32_bf16 v[58:61], v[158:161], v[182:185], v[58:61]
	v_mfma_f32_16x16x32_bf16 v[54:57], v[166:169], v[182:185], v[54:57]
	v_mfma_f32_16x16x32_bf16 v[54:57], v[170:173], v[186:189], v[54:57]
	v_mfma_f32_16x16x32_bf16 v[38:41], v[170:173], v[194:197], v[38:41]
	v_mfma_f32_16x16x32_bf16 v[38:41], v[166:169], v[190:193], v[38:41]
	v_mfma_f32_16x16x32_bf16 v[22:25], v[166:169], v[198:201], v[22:25]
	v_mfma_f32_16x16x32_bf16 v[22:25], v[170:173], v[202:205], v[22:25]
	v_mfma_f32_16x16x32_bf16 v[6:9], v[170:173], v[210:213], v[6:9]
	v_mfma_f32_16x16x32_bf16 v[6:9], v[166:169], v[206:209], v[6:9]
	v_mfma_f32_16x16x32_bf16 v[2:5], v[174:177], v[206:209], v[2:5]
	v_mfma_f32_16x16x32_bf16 v[2:5], v[178:181], v[210:213], v[2:5]
	v_mfma_f32_16x16x32_bf16 v[18:21], v[178:181], v[202:205], v[18:21]
	v_mfma_f32_16x16x32_bf16 v[18:21], v[174:177], v[198:201], v[18:21]
	s_setprio 1
	s_barrier
	v_mfma_f32_16x16x32_bf16 v[34:37], v[174:177], v[190:193], v[34:37]
	v_mfma_f32_16x16x32_bf16 v[34:37], v[178:181], v[194:197], v[34:37]
	v_mfma_f32_16x16x32_bf16 v[50:53], v[178:181], v[186:189], v[50:53]
	v_mfma_f32_16x16x32_bf16 v[50:53], v[174:177], v[182:185], v[50:53]
	s_setprio 0
	v_add_u32_e32 v162, s70, v1
	v_add_u32_e32 v178, s71, v1
	ds_read_b128 v[150:153], v162
	ds_read_b128 v[154:157], v162 offset:1024
	ds_read_b128 v[158:161], v162 offset:2048
	ds_read_b128 v[162:165], v162 offset:3072
	ds_read_b128 v[166:169], v178
	ds_read_b128 v[170:173], v178 offset:1024
	ds_read_b128 v[174:177], v178 offset:2048
	ds_read_b128 v[178:181], v178 offset:3072
	s_add_u32 s22, s28, 0x18000
	s_addc_u32 s23, s29, 0
	s_mov_b32 m0, s52
	ds_read_b128 v[182:185], v149 offset:32768
	ds_read_b128 v[186:189], v149 offset:33792
	ds_read_b128 v[190:193], v149 offset:34816
	ds_read_b128 v[194:197], v149 offset:35840
	ds_read_b128 v[198:201], v149 offset:36864
	ds_read_b128 v[202:205], v149 offset:37888
	ds_read_b128 v[206:209], v149 offset:38912
	ds_read_b128 v[210:213], v149 offset:39936
	global_load_lds_dwordx4 v136, s[22:23]
	s_mov_b32 m0, s53
	s_nop 0
	global_load_lds_dwordx4 v132, s[22:23]
	s_waitcnt vmcnt(8)
	s_waitcnt lgkmcnt(0)
	s_barrier
	v_mfma_f32_16x16x32_bf16 v[126:129], v[150:153], v[182:185], v[126:129]
	v_mfma_f32_16x16x32_bf16 v[126:129], v[154:157], v[186:189], v[126:129]
	v_mfma_f32_16x16x32_bf16 v[110:113], v[154:157], v[194:197], v[110:113]
	v_mfma_f32_16x16x32_bf16 v[110:113], v[150:153], v[190:193], v[110:113]
	v_mfma_f32_16x16x32_bf16 v[94:97], v[150:153], v[198:201], v[94:97]
	v_mfma_f32_16x16x32_bf16 v[94:97], v[154:157], v[202:205], v[94:97]
	v_mfma_f32_16x16x32_bf16 v[78:81], v[154:157], v[210:213], v[78:81]
	v_mfma_f32_16x16x32_bf16 v[78:81], v[150:153], v[206:209], v[78:81]
	v_mfma_f32_16x16x32_bf16 v[74:77], v[158:161], v[206:209], v[74:77]
	v_mfma_f32_16x16x32_bf16 v[74:77], v[162:165], v[210:213], v[74:77]
	v_mfma_f32_16x16x32_bf16 v[90:93], v[162:165], v[202:205], v[90:93]
	v_mfma_f32_16x16x32_bf16 v[90:93], v[158:161], v[198:201], v[90:93]
	v_mfma_f32_16x16x32_bf16 v[106:109], v[158:161], v[190:193], v[106:109]
	v_mfma_f32_16x16x32_bf16 v[106:109], v[162:165], v[194:197], v[106:109]
	v_mfma_f32_16x16x32_bf16 v[122:125], v[162:165], v[186:189], v[122:125]
	v_mfma_f32_16x16x32_bf16 v[122:125], v[158:161], v[182:185], v[122:125]
	v_mfma_f32_16x16x32_bf16 v[118:121], v[166:169], v[182:185], v[118:121]
	v_mfma_f32_16x16x32_bf16 v[118:121], v[170:173], v[186:189], v[118:121]
	v_mfma_f32_16x16x32_bf16 v[102:105], v[170:173], v[194:197], v[102:105]
	v_mfma_f32_16x16x32_bf16 v[102:105], v[166:169], v[190:193], v[102:105]
	v_mfma_f32_16x16x32_bf16 v[86:89], v[166:169], v[198:201], v[86:89]
	v_mfma_f32_16x16x32_bf16 v[86:89], v[170:173], v[202:205], v[86:89]
	v_mfma_f32_16x16x32_bf16 v[70:73], v[170:173], v[210:213], v[70:73]
	v_mfma_f32_16x16x32_bf16 v[70:73], v[166:169], v[206:209], v[70:73]
	v_mfma_f32_16x16x32_bf16 v[66:69], v[174:177], v[206:209], v[66:69]
	v_mfma_f32_16x16x32_bf16 v[66:69], v[178:181], v[210:213], v[66:69]
	v_mfma_f32_16x16x32_bf16 v[82:85], v[178:181], v[202:205], v[82:85]
	v_mfma_f32_16x16x32_bf16 v[82:85], v[174:177], v[198:201], v[82:85]
	s_setprio 1
	s_barrier
	v_mfma_f32_16x16x32_bf16 v[98:101], v[174:177], v[190:193], v[98:101]
	v_mfma_f32_16x16x32_bf16 v[98:101], v[178:181], v[194:197], v[98:101]
	v_mfma_f32_16x16x32_bf16 v[114:117], v[178:181], v[186:189], v[114:117]
	v_mfma_f32_16x16x32_bf16 v[114:117], v[174:177], v[182:185], v[114:117]
	s_setprio 0
	s_mov_b32 m0, s72
	ds_read_b128 v[182:185], v149 offset:49152
	ds_read_b128 v[186:189], v149 offset:50176
	ds_read_b128 v[190:193], v149 offset:51200
	ds_read_b128 v[194:197], v149 offset:52224
	ds_read_b128 v[198:201], v149 offset:53248
	ds_read_b128 v[202:205], v149 offset:54272
	ds_read_b128 v[206:209], v149 offset:55296
	ds_read_b128 v[210:213], v149 offset:56320
	s_add_u32 s98, s26, s4
	s_addc_u32 s99, s27, s5
	global_load_lds_dwordx4 v134, s[98:99]
	s_add_i32 m0, s72, 0x2000
	s_add_u32 s22, s26, 0x18080
	v_lshl_add_u64 v[144:145], v[214:215], 0, s[4:5]
	s_addc_u32 s23, s27, 0
	s_add_i32 s26, s71, s30
	global_load_lds_dwordx4 v[144:145], off
	s_mov_b32 m0, s26
	s_nop 0
	global_load_lds_dwordx4 v134, s[22:23]
	s_add_i32 m0, s26, 0x2000
	s_nop 0
	global_load_lds_dwordx4 v130, s[22:23]
	s_mov_b32 m0, s59
	s_nop 0
	s_add_u32 s100, s28, s4
	s_addc_u32 s101, s29, s5
	global_load_lds_dwordx4 v136, s[100:101]
	s_mov_b32 m0, s60
	s_nop 0
	s_add_u32 s98, s28, s4
	s_addc_u32 s99, s29, s5
	global_load_lds_dwordx4 v132, s[98:99]
	s_waitcnt vmcnt(8)
	s_waitcnt lgkmcnt(0)
	s_barrier
	v_mfma_f32_16x16x32_bf16 v[62:65], v[150:153], v[182:185], v[62:65]
	v_mfma_f32_16x16x32_bf16 v[62:65], v[154:157], v[186:189], v[62:65]
	v_mfma_f32_16x16x32_bf16 v[46:49], v[154:157], v[194:197], v[46:49]
	v_mfma_f32_16x16x32_bf16 v[46:49], v[150:153], v[190:193], v[46:49]
	v_mfma_f32_16x16x32_bf16 v[30:33], v[150:153], v[198:201], v[30:33]
	v_mfma_f32_16x16x32_bf16 v[30:33], v[154:157], v[202:205], v[30:33]
	v_mfma_f32_16x16x32_bf16 v[14:17], v[154:157], v[210:213], v[14:17]
	v_mfma_f32_16x16x32_bf16 v[14:17], v[150:153], v[206:209], v[14:17]
	v_mfma_f32_16x16x32_bf16 v[10:13], v[158:161], v[206:209], v[10:13]
	v_mfma_f32_16x16x32_bf16 v[10:13], v[162:165], v[210:213], v[10:13]
	v_mfma_f32_16x16x32_bf16 v[26:29], v[162:165], v[202:205], v[26:29]
	v_mfma_f32_16x16x32_bf16 v[26:29], v[158:161], v[198:201], v[26:29]
	v_mfma_f32_16x16x32_bf16 v[42:45], v[158:161], v[190:193], v[42:45]
	v_mfma_f32_16x16x32_bf16 v[42:45], v[162:165], v[194:197], v[42:45]
	v_mfma_f32_16x16x32_bf16 v[58:61], v[162:165], v[186:189], v[58:61]
	v_mfma_f32_16x16x32_bf16 v[58:61], v[158:161], v[182:185], v[58:61]
	v_mfma_f32_16x16x32_bf16 v[54:57], v[166:169], v[182:185], v[54:57]
	v_mfma_f32_16x16x32_bf16 v[54:57], v[170:173], v[186:189], v[54:57]
	v_mfma_f32_16x16x32_bf16 v[38:41], v[170:173], v[194:197], v[38:41]
	v_mfma_f32_16x16x32_bf16 v[38:41], v[166:169], v[190:193], v[38:41]
	v_mfma_f32_16x16x32_bf16 v[22:25], v[166:169], v[198:201], v[22:25]
	v_mfma_f32_16x16x32_bf16 v[22:25], v[170:173], v[202:205], v[22:25]
	v_mfma_f32_16x16x32_bf16 v[6:9], v[170:173], v[210:213], v[6:9]
	v_mfma_f32_16x16x32_bf16 v[6:9], v[166:169], v[206:209], v[6:9]
	v_mfma_f32_16x16x32_bf16 v[2:5], v[174:177], v[206:209], v[2:5]
	v_mfma_f32_16x16x32_bf16 v[2:5], v[178:181], v[210:213], v[2:5]
	v_mfma_f32_16x16x32_bf16 v[18:21], v[178:181], v[202:205], v[18:21]
	v_mfma_f32_16x16x32_bf16 v[18:21], v[174:177], v[198:201], v[18:21]
	s_setprio 1
	s_barrier
	v_mfma_f32_16x16x32_bf16 v[34:37], v[174:177], v[190:193], v[34:37]
	v_mfma_f32_16x16x32_bf16 v[34:37], v[178:181], v[194:197], v[34:37]
	v_mfma_f32_16x16x32_bf16 v[50:53], v[178:181], v[186:189], v[50:53]
	v_mfma_f32_16x16x32_bf16 v[50:53], v[174:177], v[182:185], v[50:53]
	s_setprio 0
	s_add_u32 s75, s75, 0x100
	s_addc_u32 s76, s76, 0
	s_cmp_ge_i32 s77, s57
	s_mov_b64 s[22:23], s[24:25]
	s_mov_b32 s26, s77
	s_cbranch_scc0 .LBB0_468

.LBB0_599:
	v_add_u32_e32 v142, s74, v199
	v_add_u32_e32 v162, s75, v199
	ds_read_b128 v[130:133], v142
	ds_read_b128 v[134:137], v142 offset:1024
	ds_read_b128 v[138:141], v142 offset:2048
	ds_read_b128 v[142:145], v142 offset:3072
	ds_read_b128 v[146:149], v162
	ds_read_b128 v[150:153], v162 offset:1024
	ds_read_b128 v[174:177], v162 offset:2048
	ds_read_b128 v[178:181], v162 offset:3072
	s_add_i32 s31, s52, 2
	s_add_u32 s50, s34, 0x3ff000
	s_addc_u32 s51, s35, 0
	s_cmp_eq_u32 s71, s52
	s_cselect_b32 s56, s26, s50
	s_cselect_b32 s57, s27, s51
	s_cselect_b32 s54, s28, s23
	s_cselect_b32 s55, s29, s25
	s_add_u32 s52, s56, 0x400000
	s_addc_u32 s53, s57, 0
	s_add_i32 m0, s59, 0xc000
	ds_read_b128 v[182:185], v200
	ds_read_b128 v[186:189], v200 offset:1024
	ds_read_b128 v[190:193], v200 offset:2048
	ds_read_b128 v[194:197], v200 offset:3072
	ds_read_b128 v[202:205], v200 offset:4096
	ds_read_b128 v[206:209], v200 offset:5120
	ds_read_b128 v[210:213], v200 offset:6144
	ds_read_b128 v[214:217], v200 offset:7168
	global_load_lds_dwordx4 v164, s[34:35]
	s_add_i32 m0, s59, 0xe000
	s_nop 0
	global_load_lds_dwordx4 v166, s[34:35]
	s_waitcnt vmcnt(8)
	s_waitcnt lgkmcnt(0)
	s_barrier
	v_mfma_f32_16x16x32_bf16 v[118:121], v[130:133], v[182:185], v[118:121]
	v_mfma_f32_16x16x32_bf16 v[118:121], v[134:137], v[186:189], v[118:121]
	v_mfma_f32_16x16x32_bf16 v[110:113], v[134:137], v[194:197], v[110:113]
	v_mfma_f32_16x16x32_bf16 v[110:113], v[130:133], v[190:193], v[110:113]
	v_mfma_f32_16x16x32_bf16 v[94:97], v[130:133], v[202:205], v[94:97]
	v_mfma_f32_16x16x32_bf16 v[94:97], v[134:137], v[206:209], v[94:97]
	v_mfma_f32_16x16x32_bf16 v[78:81], v[134:137], v[214:217], v[78:81]
	v_mfma_f32_16x16x32_bf16 v[78:81], v[130:133], v[210:213], v[78:81]
	v_mfma_f32_16x16x32_bf16 v[74:77], v[138:141], v[210:213], v[74:77]
	v_mfma_f32_16x16x32_bf16 v[74:77], v[142:145], v[214:217], v[74:77]
	v_mfma_f32_16x16x32_bf16 v[90:93], v[142:145], v[206:209], v[90:93]
	v_mfma_f32_16x16x32_bf16 v[90:93], v[138:141], v[202:205], v[90:93]
	v_mfma_f32_16x16x32_bf16 v[106:109], v[138:141], v[190:193], v[106:109]
	v_mfma_f32_16x16x32_bf16 v[106:109], v[142:145], v[194:197], v[106:109]
	v_mfma_f32_16x16x32_bf16 v[122:125], v[142:145], v[186:189], v[122:125]
	v_mfma_f32_16x16x32_bf16 v[122:125], v[138:141], v[182:185], v[122:125]
	v_mfma_f32_16x16x32_bf16 v[126:129], v[146:149], v[182:185], v[126:129]
	v_mfma_f32_16x16x32_bf16 v[126:129], v[150:153], v[186:189], v[126:129]
	v_mfma_f32_16x16x32_bf16 v[102:105], v[150:153], v[194:197], v[102:105]
	v_mfma_f32_16x16x32_bf16 v[102:105], v[146:149], v[190:193], v[102:105]
	v_mfma_f32_16x16x32_bf16 v[86:89], v[146:149], v[202:205], v[86:89]
	v_mfma_f32_16x16x32_bf16 v[86:89], v[150:153], v[206:209], v[86:89]
	v_mfma_f32_16x16x32_bf16 v[70:73], v[150:153], v[214:217], v[70:73]
	v_mfma_f32_16x16x32_bf16 v[70:73], v[146:149], v[210:213], v[70:73]
	v_mfma_f32_16x16x32_bf16 v[66:69], v[174:177], v[210:213], v[66:69]
	v_mfma_f32_16x16x32_bf16 v[66:69], v[178:181], v[214:217], v[66:69]
	v_mfma_f32_16x16x32_bf16 v[82:85], v[178:181], v[206:209], v[82:85]
	v_mfma_f32_16x16x32_bf16 v[82:85], v[174:177], v[202:205], v[82:85]
	s_setprio 1
	s_barrier
	v_mfma_f32_16x16x32_bf16 v[98:101], v[174:177], v[190:193], v[98:101]
	v_mfma_f32_16x16x32_bf16 v[98:101], v[178:181], v[194:197], v[98:101]
	v_mfma_f32_16x16x32_bf16 v[114:117], v[178:181], v[186:189], v[114:117]
	v_mfma_f32_16x16x32_bf16 v[114:117], v[174:177], v[182:185], v[114:117]
	s_setprio 0
	s_add_i32 s50, s74, s41
	s_mov_b32 m0, s50
	ds_read_b128 v[182:185], v200 offset:16384
	ds_read_b128 v[186:189], v200 offset:17408
	ds_read_b128 v[190:193], v200 offset:18432
	ds_read_b128 v[194:197], v200 offset:19456
	ds_read_b128 v[202:205], v200 offset:20480
	ds_read_b128 v[206:209], v200 offset:21504
	ds_read_b128 v[210:213], v200 offset:22528
	ds_read_b128 v[214:217], v200 offset:23552
	global_load_lds_dwordx4 v156, s[54:55]
	s_add_i32 m0, s50, 0x2000
	s_add_u32 s50, s54, 0x20000
	v_lshl_add_u64 v[220:221], s[54:55], 0, v[160:161]
	s_addc_u32 s51, s55, 0
	s_add_i32 s78, s75, s41
	global_load_lds_dwordx4 v160, s[54:55]
	s_mov_b32 m0, s78
	s_nop 0
	global_load_lds_dwordx4 v156, s[50:51]
	s_add_i32 m0, s78, 0x2000
	s_nop 0
	global_load_lds_dwordx4 v160, s[50:51]
	s_mov_b32 m0, s59
	s_nop 0
	global_load_lds_dwordx4 v154, s[56:57]
	s_mov_b32 m0, s60
	s_nop 0
	global_load_lds_dwordx4 v158, s[56:57]
	s_waitcnt vmcnt(8)
	s_waitcnt lgkmcnt(0)
	s_barrier
	v_mfma_f32_16x16x32_bf16 v[62:65], v[130:133], v[182:185], v[62:65]
	v_mfma_f32_16x16x32_bf16 v[62:65], v[134:137], v[186:189], v[62:65]
	v_mfma_f32_16x16x32_bf16 v[46:49], v[134:137], v[194:197], v[46:49]
	v_mfma_f32_16x16x32_bf16 v[46:49], v[130:133], v[190:193], v[46:49]
	v_mfma_f32_16x16x32_bf16 v[30:33], v[130:133], v[202:205], v[30:33]
	v_mfma_f32_16x16x32_bf16 v[30:33], v[134:137], v[206:209], v[30:33]
	v_mfma_f32_16x16x32_bf16 v[14:17], v[134:137], v[214:217], v[14:17]
	v_mfma_f32_16x16x32_bf16 v[14:17], v[130:133], v[210:213], v[14:17]
	v_mfma_f32_16x16x32_bf16 v[10:13], v[138:141], v[210:213], v[10:13]
	v_mfma_f32_16x16x32_bf16 v[10:13], v[142:145], v[214:217], v[10:13]
	v_mfma_f32_16x16x32_bf16 v[26:29], v[142:145], v[206:209], v[26:29]
	v_mfma_f32_16x16x32_bf16 v[26:29], v[138:141], v[202:205], v[26:29]
	v_mfma_f32_16x16x32_bf16 v[42:45], v[138:141], v[190:193], v[42:45]
	v_mfma_f32_16x16x32_bf16 v[42:45], v[142:145], v[194:197], v[42:45]
	v_mfma_f32_16x16x32_bf16 v[58:61], v[142:145], v[186:189], v[58:61]
	v_mfma_f32_16x16x32_bf16 v[58:61], v[138:141], v[182:185], v[58:61]
	v_mfma_f32_16x16x32_bf16 v[54:57], v[146:149], v[182:185], v[54:57]
	v_mfma_f32_16x16x32_bf16 v[54:57], v[150:153], v[186:189], v[54:57]
	v_mfma_f32_16x16x32_bf16 v[38:41], v[150:153], v[194:197], v[38:41]
	v_mfma_f32_16x16x32_bf16 v[38:41], v[146:149], v[190:193], v[38:41]
	v_mfma_f32_16x16x32_bf16 v[22:25], v[146:149], v[202:205], v[22:25]
	v_mfma_f32_16x16x32_bf16 v[22:25], v[150:153], v[206:209], v[22:25]
	v_mfma_f32_16x16x32_bf16 v[6:9], v[150:153], v[214:217], v[6:9]
	v_mfma_f32_16x16x32_bf16 v[6:9], v[146:149], v[210:213], v[6:9]
	v_mfma_f32_16x16x32_bf16 v[2:5], v[174:177], v[210:213], v[2:5]
	v_mfma_f32_16x16x32_bf16 v[2:5], v[178:181], v[214:217], v[2:5]
	v_mfma_f32_16x16x32_bf16 v[18:21], v[178:181], v[206:209], v[18:21]
	v_mfma_f32_16x16x32_bf16 v[18:21], v[174:177], v[202:205], v[18:21]
	s_setprio 1
	s_barrier
	v_mfma_f32_16x16x32_bf16 v[34:37], v[174:177], v[190:193], v[34:37]
	v_mfma_f32_16x16x32_bf16 v[34:37], v[178:181], v[194:197], v[34:37]
	v_mfma_f32_16x16x32_bf16 v[50:53], v[178:181], v[186:189], v[50:53]
	v_mfma_f32_16x16x32_bf16 v[50:53], v[174:177], v[182:185], v[50:53]
	s_setprio 0
	s_add_i32 s78, 0, 0x18000
	s_add_i32 s79, 0, 0x1c000
	v_add_u32_e32 v142, s78, v199
	v_add_u32_e32 v162, s79, v199
	ds_read_b128 v[130:133], v142
	ds_read_b128 v[134:137], v142 offset:1024
	ds_read_b128 v[138:141], v142 offset:2048
	ds_read_b128 v[142:145], v142 offset:3072
	ds_read_b128 v[146:149], v162
	ds_read_b128 v[150:153], v162 offset:1024
	ds_read_b128 v[174:177], v162 offset:2048
	ds_read_b128 v[178:181], v162 offset:3072
	s_add_u32 s50, s56, 0x1000
	s_addc_u32 s51, s57, 0
	s_mov_b32 m0, s61
	ds_read_b128 v[182:185], v200 offset:32768
	ds_read_b128 v[186:189], v200 offset:33792
	ds_read_b128 v[190:193], v200 offset:34816
	ds_read_b128 v[194:197], v200 offset:35840
	ds_read_b128 v[202:205], v200 offset:36864
	ds_read_b128 v[206:209], v200 offset:37888
	ds_read_b128 v[210:213], v200 offset:38912
	ds_read_b128 v[214:217], v200 offset:39936
	global_load_lds_dwordx4 v154, s[50:51]
	s_mov_b32 m0, s62
	s_nop 0
	global_load_lds_dwordx4 v158, s[50:51]
	s_waitcnt vmcnt(8)
	s_waitcnt lgkmcnt(0)
	s_barrier
	v_mfma_f32_16x16x32_bf16 v[118:121], v[130:133], v[182:185], v[118:121]
	v_mfma_f32_16x16x32_bf16 v[118:121], v[134:137], v[186:189], v[118:121]
	v_mfma_f32_16x16x32_bf16 v[110:113], v[134:137], v[194:197], v[110:113]
	v_mfma_f32_16x16x32_bf16 v[110:113], v[130:133], v[190:193], v[110:113]
	v_mfma_f32_16x16x32_bf16 v[94:97], v[130:133], v[202:205], v[94:97]
	v_mfma_f32_16x16x32_bf16 v[94:97], v[134:137], v[206:209], v[94:97]
	v_mfma_f32_16x16x32_bf16 v[78:81], v[134:137], v[214:217], v[78:81]
	v_mfma_f32_16x16x32_bf16 v[78:81], v[130:133], v[210:213], v[78:81]
	v_mfma_f32_16x16x32_bf16 v[74:77], v[138:141], v[210:213], v[74:77]
	v_mfma_f32_16x16x32_bf16 v[74:77], v[142:145], v[214:217], v[74:77]
	v_mfma_f32_16x16x32_bf16 v[90:93], v[142:145], v[206:209], v[90:93]
	v_mfma_f32_16x16x32_bf16 v[90:93], v[138:141], v[202:205], v[90:93]
	v_mfma_f32_16x16x32_bf16 v[106:109], v[138:141], v[190:193], v[106:109]
	v_mfma_f32_16x16x32_bf16 v[106:109], v[142:145], v[194:197], v[106:109]
	v_mfma_f32_16x16x32_bf16 v[122:125], v[142:145], v[186:189], v[122:125]
	v_mfma_f32_16x16x32_bf16 v[122:125], v[138:141], v[182:185], v[122:125]
	v_mfma_f32_16x16x32_bf16 v[126:129], v[146:149], v[182:185], v[126:129]
	v_mfma_f32_16x16x32_bf16 v[126:129], v[150:153], v[186:189], v[126:129]
	v_mfma_f32_16x16x32_bf16 v[102:105], v[150:153], v[194:197], v[102:105]
	v_mfma_f32_16x16x32_bf16 v[102:105], v[146:149], v[190:193], v[102:105]
	v_mfma_f32_16x16x32_bf16 v[86:89], v[146:149], v[202:205], v[86:89]
	v_mfma_f32_16x16x32_bf16 v[86:89], v[150:153], v[206:209], v[86:89]
	v_mfma_f32_16x16x32_bf16 v[70:73], v[150:153], v[214:217], v[70:73]
	v_mfma_f32_16x16x32_bf16 v[70:73], v[146:149], v[210:213], v[70:73]
	v_mfma_f32_16x16x32_bf16 v[66:69], v[174:177], v[210:213], v[66:69]
	v_mfma_f32_16x16x32_bf16 v[66:69], v[178:181], v[214:217], v[66:69]
	v_mfma_f32_16x16x32_bf16 v[82:85], v[178:181], v[206:209], v[82:85]
	v_mfma_f32_16x16x32_bf16 v[82:85], v[174:177], v[202:205], v[82:85]
	s_setprio 1
	s_barrier
	v_mfma_f32_16x16x32_bf16 v[98:101], v[174:177], v[190:193], v[98:101]
	v_mfma_f32_16x16x32_bf16 v[98:101], v[178:181], v[194:197], v[98:101]
	v_mfma_f32_16x16x32_bf16 v[114:117], v[178:181], v[186:189], v[114:117]
	v_mfma_f32_16x16x32_bf16 v[114:117], v[174:177], v[182:185], v[114:117]
	s_setprio 0
	s_add_i32 s50, s78, s41
	s_mov_b32 m0, s50
	ds_read_b128 v[182:185], v200 offset:49152
	ds_read_b128 v[186:189], v200 offset:50176
	ds_read_b128 v[190:193], v200 offset:51200
	ds_read_b128 v[194:197], v200 offset:52224
	ds_read_b128 v[202:205], v200 offset:53248
	ds_read_b128 v[206:209], v200 offset:54272
	ds_read_b128 v[210:213], v200 offset:55296
	ds_read_b128 v[214:217], v200 offset:56320
	s_add_u32 s98, s54, s14
	s_addc_u32 s99, s55, s15
	global_load_lds_dwordx4 v156, s[98:99]
	s_add_i32 m0, s50, 0x2000
	s_add_u32 s50, s54, 0x20080
	v_lshl_add_u64 v[218:219], v[220:221], 0, s[14:15]
	s_addc_u32 s51, s55, 0
	s_add_i32 s54, s79, s41
	global_load_lds_dwordx4 v[218:219], off
	s_mov_b32 m0, s54
	s_nop 0
	global_load_lds_dwordx4 v156, s[50:51]
	s_add_i32 m0, s54, 0x2000
	s_nop 0
	global_load_lds_dwordx4 v160, s[50:51]
	s_mov_b32 m0, s69
	s_nop 0
	global_load_lds_dwordx4 v154, s[52:53]
	s_mov_b32 m0, s70
	s_nop 0
	global_load_lds_dwordx4 v158, s[52:53]
	s_waitcnt vmcnt(8)
	s_waitcnt lgkmcnt(0)
	s_barrier
	v_mfma_f32_16x16x32_bf16 v[62:65], v[130:133], v[182:185], v[62:65]
	v_mfma_f32_16x16x32_bf16 v[62:65], v[134:137], v[186:189], v[62:65]
	v_mfma_f32_16x16x32_bf16 v[46:49], v[134:137], v[194:197], v[46:49]
	v_mfma_f32_16x16x32_bf16 v[46:49], v[130:133], v[190:193], v[46:49]
	v_mfma_f32_16x16x32_bf16 v[30:33], v[130:133], v[202:205], v[30:33]
	v_mfma_f32_16x16x32_bf16 v[30:33], v[134:137], v[206:209], v[30:33]
	v_mfma_f32_16x16x32_bf16 v[14:17], v[134:137], v[214:217], v[14:17]
	v_mfma_f32_16x16x32_bf16 v[14:17], v[130:133], v[210:213], v[14:17]
	v_mfma_f32_16x16x32_bf16 v[10:13], v[138:141], v[210:213], v[10:13]
	v_mfma_f32_16x16x32_bf16 v[10:13], v[142:145], v[214:217], v[10:13]
	v_mfma_f32_16x16x32_bf16 v[26:29], v[142:145], v[206:209], v[26:29]
	v_mfma_f32_16x16x32_bf16 v[26:29], v[138:141], v[202:205], v[26:29]
	v_mfma_f32_16x16x32_bf16 v[42:45], v[138:141], v[190:193], v[42:45]
	v_mfma_f32_16x16x32_bf16 v[42:45], v[142:145], v[194:197], v[42:45]
	v_mfma_f32_16x16x32_bf16 v[58:61], v[142:145], v[186:189], v[58:61]
	v_mfma_f32_16x16x32_bf16 v[58:61], v[138:141], v[182:185], v[58:61]
	v_mfma_f32_16x16x32_bf16 v[54:57], v[146:149], v[182:185], v[54:57]
	v_mfma_f32_16x16x32_bf16 v[54:57], v[150:153], v[186:189], v[54:57]
	v_mfma_f32_16x16x32_bf16 v[38:41], v[150:153], v[194:197], v[38:41]
	v_mfma_f32_16x16x32_bf16 v[38:41], v[146:149], v[190:193], v[38:41]
	v_mfma_f32_16x16x32_bf16 v[22:25], v[146:149], v[202:205], v[22:25]
	v_mfma_f32_16x16x32_bf16 v[22:25], v[150:153], v[206:209], v[22:25]
	v_mfma_f32_16x16x32_bf16 v[6:9], v[150:153], v[214:217], v[6:9]
	v_mfma_f32_16x16x32_bf16 v[6:9], v[146:149], v[210:213], v[6:9]
	v_mfma_f32_16x16x32_bf16 v[2:5], v[174:177], v[210:213], v[2:5]
	v_mfma_f32_16x16x32_bf16 v[2:5], v[178:181], v[214:217], v[2:5]
	v_mfma_f32_16x16x32_bf16 v[18:21], v[178:181], v[206:209], v[18:21]
	v_mfma_f32_16x16x32_bf16 v[18:21], v[174:177], v[202:205], v[18:21]
	s_setprio 1
	s_barrier
	v_mfma_f32_16x16x32_bf16 v[34:37], v[174:177], v[190:193], v[34:37]
	v_mfma_f32_16x16x32_bf16 v[34:37], v[178:181], v[194:197], v[34:37]
	v_mfma_f32_16x16x32_bf16 v[50:53], v[178:181], v[186:189], v[50:53]
	v_mfma_f32_16x16x32_bf16 v[50:53], v[174:177], v[182:185], v[50:53]
	s_setprio 0
	s_add_u32 s23, s23, 0x100
	s_addc_u32 s25, s25, 0
	s_add_u32 s34, s34, 0x800000
	s_addc_u32 s35, s35, 0
	s_cmp_ge_i32 s31, s67
	s_mov_b32 s52, s31
	s_cbranch_scc0 .LBB0_599

.LBB0_740:
	v_add_u32_e32 v144, s88, v188
	v_add_u32_e32 v160, s89, v188
	ds_read_b128 v[132:135], v144
	ds_read_b128 v[136:139], v144 offset:1024
	ds_read_b128 v[140:143], v144 offset:2048
	ds_read_b128 v[144:147], v144 offset:3072
	ds_read_b128 v[148:151], v160
	ds_read_b128 v[152:155], v160 offset:1024
	ds_read_b128 v[156:159], v160 offset:2048
	ds_read_b128 v[184:187], v160 offset:3072
	s_add_i32 s92, s55, 2
	s_add_u32 s50, s60, 0x3fc000
	s_addc_u32 s51, s61, 0
	s_cmp_eq_u32 s87, s55
	s_cselect_b32 s70, s64, s50
	s_cselect_b32 s71, s65, s51
	s_cselect_b32 s69, s67, s53
	s_cselect_b32 s68, s66, s13
	s_add_u32 s62, s70, 0x400000
	s_addc_u32 s63, s71, 0
	s_add_i32 m0, s77, 0xc000
	ds_read_b128 v[192:195], v189
	ds_read_b128 v[196:199], v189 offset:1024
	ds_read_b128 v[200:203], v189 offset:2048
	ds_read_b128 v[204:207], v189 offset:3072
	ds_read_b128 v[208:211], v189 offset:4096
	ds_read_b128 v[212:215], v189 offset:5120
	ds_read_b128 v[216:219], v189 offset:6144
	ds_read_b128 v[220:223], v189 offset:7168
	global_load_lds_dwordx4 v176, s[60:61]
	s_add_i32 m0, s77, 0xe000
	s_nop 0
	global_load_lds_dwordx4 v178, s[60:61]
	s_waitcnt vmcnt(8)
	s_waitcnt lgkmcnt(0)
	s_barrier
	v_mfma_f32_16x16x32_bf16 v[30:33], v[132:135], v[192:195], v[30:33]
	v_mfma_f32_16x16x32_bf16 v[30:33], v[136:139], v[196:199], v[30:33]
	v_mfma_f32_16x16x32_bf16 v[86:89], v[136:139], v[204:207], v[86:89]
	v_mfma_f32_16x16x32_bf16 v[86:89], v[132:135], v[200:203], v[86:89]
	v_mfma_f32_16x16x32_bf16 v[94:97], v[132:135], v[208:211], v[94:97]
	v_mfma_f32_16x16x32_bf16 v[94:97], v[136:139], v[212:215], v[94:97]
	v_mfma_f32_16x16x32_bf16 v[90:93], v[136:139], v[220:223], v[90:93]
	v_mfma_f32_16x16x32_bf16 v[90:93], v[132:135], v[216:219], v[90:93]
	v_mfma_f32_16x16x32_bf16 v[78:81], v[140:143], v[216:219], v[78:81]
	v_mfma_f32_16x16x32_bf16 v[78:81], v[144:147], v[220:223], v[78:81]
	v_mfma_f32_16x16x32_bf16 v[82:85], v[144:147], v[212:215], v[82:85]
	v_mfma_f32_16x16x32_bf16 v[82:85], v[140:143], v[208:211], v[82:85]
	v_mfma_f32_16x16x32_bf16 v[66:69], v[140:143], v[200:203], v[66:69]
	v_mfma_f32_16x16x32_bf16 v[66:69], v[144:147], v[204:207], v[66:69]
	v_mfma_f32_16x16x32_bf16 v[26:29], v[144:147], v[196:199], v[26:29]
	v_mfma_f32_16x16x32_bf16 v[26:29], v[140:143], v[192:195], v[26:29]
	v_mfma_f32_16x16x32_bf16 v[50:53], v[148:151], v[192:195], v[50:53]
	v_mfma_f32_16x16x32_bf16 v[50:53], v[152:155], v[196:199], v[50:53]
	v_mfma_f32_16x16x32_bf16 v[14:17], v[152:155], v[204:207], v[14:17]
	v_mfma_f32_16x16x32_bf16 v[14:17], v[148:151], v[200:203], v[14:17]
	v_mfma_f32_16x16x32_bf16 v[22:25], v[148:151], v[208:211], v[22:25]
	v_mfma_f32_16x16x32_bf16 v[22:25], v[152:155], v[212:215], v[22:25]
	v_mfma_f32_16x16x32_bf16 v[18:21], v[152:155], v[220:223], v[18:21]
	v_mfma_f32_16x16x32_bf16 v[18:21], v[148:151], v[216:219], v[18:21]
	v_mfma_f32_16x16x32_bf16 v[6:9], v[156:159], v[216:219], v[6:9]
	v_mfma_f32_16x16x32_bf16 v[6:9], v[184:187], v[220:223], v[6:9]
	v_mfma_f32_16x16x32_bf16 v[10:13], v[184:187], v[212:215], v[10:13]
	v_mfma_f32_16x16x32_bf16 v[10:13], v[156:159], v[208:211], v[10:13]
	s_setprio 1
	s_barrier
	v_mfma_f32_16x16x32_bf16 v[2:5], v[156:159], v[200:203], v[2:5]
	v_mfma_f32_16x16x32_bf16 v[2:5], v[184:187], v[204:207], v[2:5]
	v_mfma_f32_16x16x32_bf16 v[42:45], v[184:187], v[196:199], v[42:45]
	v_mfma_f32_16x16x32_bf16 v[42:45], v[156:159], v[192:195], v[42:45]
	s_setprio 0
	s_add_i32 s50, s88, s76
	s_mov_b32 m0, s50
	ds_read_b128 v[192:195], v189 offset:16384
	ds_read_b128 v[196:199], v189 offset:17408
	ds_read_b128 v[200:203], v189 offset:18432
	ds_read_b128 v[204:207], v189 offset:19456
	ds_read_b128 v[208:211], v189 offset:20480
	ds_read_b128 v[212:215], v189 offset:21504
	ds_read_b128 v[216:219], v189 offset:22528
	ds_read_b128 v[220:223], v189 offset:23552
	global_load_lds_dwordx4 v164, s[68:69]
	s_add_i32 m0, s50, 0x2000
	s_add_u32 s50, s68, 0x10000
	s_addc_u32 s51, s69, 0
	s_add_i32 s55, s89, s76
	global_load_lds_dwordx4 v168, s[68:69]
	s_mov_b32 m0, s55
	s_nop 0
	global_load_lds_dwordx4 v164, s[50:51]
	s_add_i32 m0, s55, 0x2000
	s_nop 0
	global_load_lds_dwordx4 v168, s[50:51]
	s_mov_b32 m0, s77
	s_nop 0
	global_load_lds_dwordx4 v162, s[70:71]
	s_mov_b32 m0, s78
	s_nop 0
	global_load_lds_dwordx4 v166, s[70:71]
	s_waitcnt vmcnt(8)
	s_waitcnt lgkmcnt(0)
	s_barrier
	v_mfma_f32_16x16x32_bf16 v[118:121], v[132:135], v[192:195], v[118:121]
	v_mfma_f32_16x16x32_bf16 v[118:121], v[136:139], v[196:199], v[118:121]
	v_mfma_f32_16x16x32_bf16 v[114:117], v[136:139], v[204:207], v[114:117]
	v_mfma_f32_16x16x32_bf16 v[114:117], v[132:135], v[200:203], v[114:117]
	v_mfma_f32_16x16x32_bf16 v[126:129], v[132:135], v[208:211], v[126:129]
	v_mfma_f32_16x16x32_bf16 v[126:129], v[136:139], v[212:215], v[126:129]
	v_mfma_f32_16x16x32_bf16 v[122:125], v[136:139], v[220:223], v[122:125]
	v_mfma_f32_16x16x32_bf16 v[122:125], v[132:135], v[216:219], v[122:125]
	v_mfma_f32_16x16x32_bf16 v[106:109], v[140:143], v[216:219], v[106:109]
	v_mfma_f32_16x16x32_bf16 v[106:109], v[144:147], v[220:223], v[106:109]
	v_mfma_f32_16x16x32_bf16 v[110:113], v[144:147], v[212:215], v[110:113]
	v_mfma_f32_16x16x32_bf16 v[110:113], v[140:143], v[208:211], v[110:113]
	v_mfma_f32_16x16x32_bf16 v[98:101], v[140:143], v[200:203], v[98:101]
	v_mfma_f32_16x16x32_bf16 v[98:101], v[144:147], v[204:207], v[98:101]
	v_mfma_f32_16x16x32_bf16 v[102:105], v[144:147], v[196:199], v[102:105]
	v_mfma_f32_16x16x32_bf16 v[102:105], v[140:143], v[192:195], v[102:105]
	v_mfma_f32_16x16x32_bf16 v[62:65], v[148:151], v[192:195], v[62:65]
	v_mfma_f32_16x16x32_bf16 v[62:65], v[152:155], v[196:199], v[62:65]
	v_mfma_f32_16x16x32_bf16 v[58:61], v[152:155], v[204:207], v[58:61]
	v_mfma_f32_16x16x32_bf16 v[58:61], v[148:151], v[200:203], v[58:61]
	v_mfma_f32_16x16x32_bf16 v[74:77], v[148:151], v[208:211], v[74:77]
	v_mfma_f32_16x16x32_bf16 v[74:77], v[152:155], v[212:215], v[74:77]
	v_mfma_f32_16x16x32_bf16 v[70:73], v[152:155], v[220:223], v[70:73]
	v_mfma_f32_16x16x32_bf16 v[70:73], v[148:151], v[216:219], v[70:73]
	v_mfma_f32_16x16x32_bf16 v[46:49], v[156:159], v[216:219], v[46:49]
	v_mfma_f32_16x16x32_bf16 v[46:49], v[184:187], v[220:223], v[46:49]
	v_mfma_f32_16x16x32_bf16 v[54:57], v[184:187], v[212:215], v[54:57]
	v_mfma_f32_16x16x32_bf16 v[54:57], v[156:159], v[208:211], v[54:57]
	s_setprio 1
	s_barrier
	v_mfma_f32_16x16x32_bf16 v[34:37], v[156:159], v[200:203], v[34:37]
	v_mfma_f32_16x16x32_bf16 v[34:37], v[184:187], v[204:207], v[34:37]
	v_mfma_f32_16x16x32_bf16 v[38:41], v[184:187], v[196:199], v[38:41]
	v_mfma_f32_16x16x32_bf16 v[38:41], v[156:159], v[192:195], v[38:41]
	s_setprio 0
	s_add_i32 s55, 0, 0x18000
	s_add_i32 s93, 0, 0x1c000
	v_add_u32_e32 v144, s55, v188
	v_add_u32_e32 v184, s93, v188
	ds_read_b128 v[132:135], v144
	ds_read_b128 v[136:139], v144 offset:1024
	ds_read_b128 v[140:143], v144 offset:2048
	ds_read_b128 v[144:147], v144 offset:3072
	ds_read_b128 v[148:151], v184
	ds_read_b128 v[152:155], v184 offset:1024
	ds_read_b128 v[156:159], v184 offset:2048
	ds_read_b128 v[184:187], v184 offset:3072
	s_add_u32 s50, s70, 0x4000
	s_addc_u32 s51, s71, 0
	s_mov_b32 m0, s79
	ds_read_b128 v[192:195], v189 offset:32768
	ds_read_b128 v[196:199], v189 offset:33792
	ds_read_b128 v[200:203], v189 offset:34816
	ds_read_b128 v[204:207], v189 offset:35840
	ds_read_b128 v[208:211], v189 offset:36864
	ds_read_b128 v[212:215], v189 offset:37888
	ds_read_b128 v[216:219], v189 offset:38912
	ds_read_b128 v[220:223], v189 offset:39936
	global_load_lds_dwordx4 v162, s[50:51]
	s_mov_b32 m0, s80
	s_nop 0
	global_load_lds_dwordx4 v166, s[50:51]
	s_waitcnt vmcnt(8)
	s_waitcnt lgkmcnt(0)
	s_barrier
	v_mfma_f32_16x16x32_bf16 v[30:33], v[132:135], v[192:195], v[30:33]
	v_mfma_f32_16x16x32_bf16 v[30:33], v[136:139], v[196:199], v[30:33]
	v_mfma_f32_16x16x32_bf16 v[86:89], v[136:139], v[204:207], v[86:89]
	v_mfma_f32_16x16x32_bf16 v[86:89], v[132:135], v[200:203], v[86:89]
	v_mfma_f32_16x16x32_bf16 v[94:97], v[132:135], v[208:211], v[94:97]
	v_mfma_f32_16x16x32_bf16 v[94:97], v[136:139], v[212:215], v[94:97]
	v_mfma_f32_16x16x32_bf16 v[90:93], v[136:139], v[220:223], v[90:93]
	v_mfma_f32_16x16x32_bf16 v[90:93], v[132:135], v[216:219], v[90:93]
	v_mfma_f32_16x16x32_bf16 v[78:81], v[140:143], v[216:219], v[78:81]
	v_mfma_f32_16x16x32_bf16 v[78:81], v[144:147], v[220:223], v[78:81]
	v_mfma_f32_16x16x32_bf16 v[82:85], v[144:147], v[212:215], v[82:85]
	v_mfma_f32_16x16x32_bf16 v[82:85], v[140:143], v[208:211], v[82:85]
	v_mfma_f32_16x16x32_bf16 v[66:69], v[140:143], v[200:203], v[66:69]
	v_mfma_f32_16x16x32_bf16 v[66:69], v[144:147], v[204:207], v[66:69]
	v_mfma_f32_16x16x32_bf16 v[26:29], v[144:147], v[196:199], v[26:29]
	v_mfma_f32_16x16x32_bf16 v[26:29], v[140:143], v[192:195], v[26:29]
	v_mfma_f32_16x16x32_bf16 v[50:53], v[148:151], v[192:195], v[50:53]
	v_mfma_f32_16x16x32_bf16 v[50:53], v[152:155], v[196:199], v[50:53]
	v_mfma_f32_16x16x32_bf16 v[14:17], v[152:155], v[204:207], v[14:17]
	v_mfma_f32_16x16x32_bf16 v[14:17], v[148:151], v[200:203], v[14:17]
	v_mfma_f32_16x16x32_bf16 v[22:25], v[148:151], v[208:211], v[22:25]
	v_mfma_f32_16x16x32_bf16 v[22:25], v[152:155], v[212:215], v[22:25]
	v_mfma_f32_16x16x32_bf16 v[18:21], v[152:155], v[220:223], v[18:21]
	v_mfma_f32_16x16x32_bf16 v[18:21], v[148:151], v[216:219], v[18:21]
	v_mfma_f32_16x16x32_bf16 v[6:9], v[156:159], v[216:219], v[6:9]
	v_mfma_f32_16x16x32_bf16 v[6:9], v[184:187], v[220:223], v[6:9]
	v_mfma_f32_16x16x32_bf16 v[10:13], v[184:187], v[212:215], v[10:13]
	v_mfma_f32_16x16x32_bf16 v[10:13], v[156:159], v[208:211], v[10:13]
	s_setprio 1
	s_barrier
	v_mfma_f32_16x16x32_bf16 v[2:5], v[156:159], v[200:203], v[2:5]
	v_mfma_f32_16x16x32_bf16 v[2:5], v[184:187], v[204:207], v[2:5]
	v_mfma_f32_16x16x32_bf16 v[42:45], v[184:187], v[196:199], v[42:45]
	v_mfma_f32_16x16x32_bf16 v[42:45], v[156:159], v[192:195], v[42:45]
	s_setprio 0
	s_add_i32 s50, s55, s76
	s_mov_b32 m0, s50
	ds_read_b128 v[192:195], v189 offset:49152
	ds_read_b128 v[196:199], v189 offset:50176
	ds_read_b128 v[200:203], v189 offset:51200
	ds_read_b128 v[204:207], v189 offset:52224
	ds_read_b128 v[208:211], v189 offset:53248
	ds_read_b128 v[212:215], v189 offset:54272
	ds_read_b128 v[216:219], v189 offset:55296
	ds_read_b128 v[220:223], v189 offset:56320
	s_add_u32 s98, s68, s14
	s_addc_u32 s99, s69, s15
	global_load_lds_dwordx4 v164, s[98:99]
	s_add_i32 m0, s50, 0x2000
	s_add_u32 s50, s68, 0x10080
	s_addc_u32 s51, s69, 0
	s_add_i32 s55, s93, s76
	s_add_u32 s100, s68, s14
	s_addc_u32 s101, s69, s15
	global_load_lds_dwordx4 v168, s[100:101]
	s_mov_b32 m0, s55
	s_nop 0
	global_load_lds_dwordx4 v164, s[50:51]
	s_add_i32 m0, s55, 0x2000
	s_nop 0
	global_load_lds_dwordx4 v168, s[50:51]
	s_mov_b32 m0, s84
	s_nop 0
	global_load_lds_dwordx4 v162, s[62:63]
	s_mov_b32 m0, s85
	s_nop 0
	global_load_lds_dwordx4 v166, s[62:63]
	s_waitcnt vmcnt(8)
	s_waitcnt lgkmcnt(0)
	s_barrier
	v_mfma_f32_16x16x32_bf16 v[118:121], v[132:135], v[192:195], v[118:121]
	v_mfma_f32_16x16x32_bf16 v[118:121], v[136:139], v[196:199], v[118:121]
	v_mfma_f32_16x16x32_bf16 v[114:117], v[136:139], v[204:207], v[114:117]
	v_mfma_f32_16x16x32_bf16 v[114:117], v[132:135], v[200:203], v[114:117]
	v_mfma_f32_16x16x32_bf16 v[126:129], v[132:135], v[208:211], v[126:129]
	v_mfma_f32_16x16x32_bf16 v[126:129], v[136:139], v[212:215], v[126:129]
	v_mfma_f32_16x16x32_bf16 v[122:125], v[136:139], v[220:223], v[122:125]
	v_mfma_f32_16x16x32_bf16 v[122:125], v[132:135], v[216:219], v[122:125]
	v_mfma_f32_16x16x32_bf16 v[106:109], v[140:143], v[216:219], v[106:109]
	v_mfma_f32_16x16x32_bf16 v[106:109], v[144:147], v[220:223], v[106:109]
	v_mfma_f32_16x16x32_bf16 v[110:113], v[144:147], v[212:215], v[110:113]
	v_mfma_f32_16x16x32_bf16 v[110:113], v[140:143], v[208:211], v[110:113]
	v_mfma_f32_16x16x32_bf16 v[98:101], v[140:143], v[200:203], v[98:101]
	v_mfma_f32_16x16x32_bf16 v[98:101], v[144:147], v[204:207], v[98:101]
	v_mfma_f32_16x16x32_bf16 v[102:105], v[144:147], v[196:199], v[102:105]
	v_mfma_f32_16x16x32_bf16 v[102:105], v[140:143], v[192:195], v[102:105]
	v_mfma_f32_16x16x32_bf16 v[62:65], v[148:151], v[192:195], v[62:65]
	v_mfma_f32_16x16x32_bf16 v[62:65], v[152:155], v[196:199], v[62:65]
	v_mfma_f32_16x16x32_bf16 v[58:61], v[152:155], v[204:207], v[58:61]
	v_mfma_f32_16x16x32_bf16 v[58:61], v[148:151], v[200:203], v[58:61]
	v_mfma_f32_16x16x32_bf16 v[74:77], v[148:151], v[208:211], v[74:77]
	v_mfma_f32_16x16x32_bf16 v[74:77], v[152:155], v[212:215], v[74:77]
	v_mfma_f32_16x16x32_bf16 v[70:73], v[152:155], v[220:223], v[70:73]
	v_mfma_f32_16x16x32_bf16 v[70:73], v[148:151], v[216:219], v[70:73]
	v_mfma_f32_16x16x32_bf16 v[46:49], v[156:159], v[216:219], v[46:49]
	v_mfma_f32_16x16x32_bf16 v[46:49], v[184:187], v[220:223], v[46:49]
	v_mfma_f32_16x16x32_bf16 v[54:57], v[184:187], v[212:215], v[54:57]
	v_mfma_f32_16x16x32_bf16 v[54:57], v[156:159], v[208:211], v[54:57]
	s_setprio 1
	s_barrier
	v_mfma_f32_16x16x32_bf16 v[34:37], v[156:159], v[200:203], v[34:37]
	v_mfma_f32_16x16x32_bf16 v[34:37], v[184:187], v[204:207], v[34:37]
	v_mfma_f32_16x16x32_bf16 v[38:41], v[184:187], v[196:199], v[38:41]
	v_mfma_f32_16x16x32_bf16 v[38:41], v[156:159], v[192:195], v[38:41]
	s_setprio 0
	s_add_u32 s13, s13, 0x100
	s_addc_u32 s53, s53, 0
	s_add_u32 s60, s60, 0x800000
	s_addc_u32 s61, s61, 0
	s_cmp_ge_i32 s92, s83
	s_cbranch_scc0 .LBB0_738

.LBB0_872:
	s_add_i32 s77, s52, 2
	s_add_u32 s50, s34, 0xfffc0080
	s_addc_u32 s51, s35, -1
	s_cmp_eq_u32 s70, s52
	s_cselect_b32 s52, s30, s21
	s_cselect_b32 s55, s29, s51
	s_cselect_b32 s54, s28, s50
	s_cselect_b32 s53, s31, s23
	ds_read_b128 v[150:153], v246
	ds_read_b128 v[154:157], v246 offset:1024
	ds_read_b128 v[158:161], v246 offset:2048
	ds_read_b128 v[162:165], v246 offset:3072
	ds_read_b128 v[166:169], v247
	ds_read_b128 v[170:173], v247 offset:1024
	ds_read_b128 v[174:177], v247 offset:2048
	ds_read_b128 v[178:181], v247 offset:3072
	ds_read_b128 v[182:185], v149
	ds_read_b128 v[186:189], v149 offset:1024
	ds_read_b128 v[190:193], v149 offset:2048
	ds_read_b128 v[194:197], v149 offset:3072
	ds_read_b128 v[198:201], v149 offset:4096
	ds_read_b128 v[202:205], v149 offset:5120
	ds_read_b128 v[206:209], v149 offset:6144
	ds_read_b128 v[210:213], v149 offset:7168
	s_add_i32 m0, s60, 0xc000
	s_nop 0
	global_load_lds_dwordx4 v132, s[34:35]
	s_add_i32 m0, s60, 0xe000
	s_nop 0
	global_load_lds_dwordx4 v134, s[34:35]
	s_waitcnt vmcnt(8)
	s_waitcnt lgkmcnt(0)
	s_barrier
	v_mfma_f32_16x16x32_bf16 v[78:81], v[150:153], v[182:185], v[78:81]
	v_mfma_f32_16x16x32_bf16 v[78:81], v[154:157], v[186:189], v[78:81]
	v_mfma_f32_16x16x32_bf16 v[66:69], v[154:157], v[194:197], v[66:69]
	v_mfma_f32_16x16x32_bf16 v[66:69], v[150:153], v[190:193], v[66:69]
	v_mfma_f32_16x16x32_bf16 v[70:73], v[150:153], v[198:201], v[70:73]
	v_mfma_f32_16x16x32_bf16 v[70:73], v[154:157], v[202:205], v[70:73]
	v_mfma_f32_16x16x32_bf16 v[74:77], v[154:157], v[210:213], v[74:77]
	v_mfma_f32_16x16x32_bf16 v[74:77], v[150:153], v[206:209], v[74:77]
	v_mfma_f32_16x16x32_bf16 v[10:13], v[158:161], v[206:209], v[10:13]
	v_mfma_f32_16x16x32_bf16 v[10:13], v[162:165], v[210:213], v[10:13]
	v_mfma_f32_16x16x32_bf16 v[6:9], v[162:165], v[202:205], v[6:9]
	v_mfma_f32_16x16x32_bf16 v[6:9], v[158:161], v[198:201], v[6:9]
	v_mfma_f32_16x16x32_bf16 v[2:5], v[158:161], v[190:193], v[2:5]
	v_mfma_f32_16x16x32_bf16 v[2:5], v[162:165], v[194:197], v[2:5]
	v_mfma_f32_16x16x32_bf16 v[14:17], v[162:165], v[186:189], v[14:17]
	v_mfma_f32_16x16x32_bf16 v[14:17], v[158:161], v[182:185], v[14:17]
	v_mfma_f32_16x16x32_bf16 v[98:101], v[166:169], v[182:185], v[98:101]
	v_mfma_f32_16x16x32_bf16 v[98:101], v[170:173], v[186:189], v[98:101]
	v_mfma_f32_16x16x32_bf16 v[82:85], v[170:173], v[194:197], v[82:85]
	v_mfma_f32_16x16x32_bf16 v[82:85], v[166:169], v[190:193], v[82:85]
	v_mfma_f32_16x16x32_bf16 v[86:89], v[166:169], v[198:201], v[86:89]
	v_mfma_f32_16x16x32_bf16 v[86:89], v[170:173], v[202:205], v[86:89]
	v_mfma_f32_16x16x32_bf16 v[94:97], v[170:173], v[210:213], v[94:97]
	v_mfma_f32_16x16x32_bf16 v[94:97], v[166:169], v[206:209], v[94:97]
	v_mfma_f32_16x16x32_bf16 v[30:33], v[174:177], v[206:209], v[30:33]
	v_mfma_f32_16x16x32_bf16 v[30:33], v[178:181], v[210:213], v[30:33]
	v_mfma_f32_16x16x32_bf16 v[22:25], v[178:181], v[202:205], v[22:25]
	v_mfma_f32_16x16x32_bf16 v[22:25], v[174:177], v[198:201], v[22:25]
	s_setprio 1
	s_barrier
	v_mfma_f32_16x16x32_bf16 v[18:21], v[174:177], v[190:193], v[18:21]
	v_mfma_f32_16x16x32_bf16 v[18:21], v[178:181], v[194:197], v[18:21]
	v_mfma_f32_16x16x32_bf16 v[34:37], v[178:181], v[186:189], v[34:37]
	v_mfma_f32_16x16x32_bf16 v[34:37], v[174:177], v[182:185], v[34:37]
	s_setprio 0
	ds_read_b128 v[182:185], v149 offset:16384
	ds_read_b128 v[186:189], v149 offset:17408
	ds_read_b128 v[190:193], v149 offset:18432
	ds_read_b128 v[194:197], v149 offset:19456
	ds_read_b128 v[198:201], v149 offset:20480
	ds_read_b128 v[202:205], v149 offset:21504
	ds_read_b128 v[206:209], v149 offset:22528
	ds_read_b128 v[210:213], v149 offset:23552
	s_add_i32 s50, s73, s15
	s_mov_b32 m0, s50
	s_nop 0
	global_load_lds_dwordx4 v228, s[52:53]
	s_add_i32 m0, s50, 0x2000
	s_add_u32 s50, s52, 0x40000
	s_addc_u32 s51, s53, 0
	s_add_i32 s78, s74, s15
	global_load_lds_dwordx4 v232, s[52:53]
	s_mov_b32 m0, s78
	s_nop 0
	global_load_lds_dwordx4 v228, s[50:51]
	s_add_i32 m0, s78, 0x2000
	s_nop 0
	global_load_lds_dwordx4 v232, s[50:51]
	s_mov_b32 m0, s60
	s_nop 0
	global_load_lds_dwordx4 v226, s[54:55]
	s_mov_b32 m0, s61
	s_nop 0
	global_load_lds_dwordx4 v230, s[54:55]
	s_waitcnt vmcnt(8)
	s_waitcnt lgkmcnt(0)
	s_barrier
	v_mfma_f32_16x16x32_bf16 v[90:93], v[150:153], v[182:185], v[90:93]
	v_mfma_f32_16x16x32_bf16 v[90:93], v[154:157], v[186:189], v[90:93]
	v_mfma_f32_16x16x32_bf16 v[102:105], v[154:157], v[194:197], v[102:105]
	v_mfma_f32_16x16x32_bf16 v[102:105], v[150:153], v[190:193], v[102:105]
	v_mfma_f32_16x16x32_bf16 v[106:109], v[150:153], v[198:201], v[106:109]
	v_mfma_f32_16x16x32_bf16 v[106:109], v[154:157], v[202:205], v[106:109]
	v_mfma_f32_16x16x32_bf16 v[110:113], v[154:157], v[210:213], v[110:113]
	v_mfma_f32_16x16x32_bf16 v[110:113], v[150:153], v[206:209], v[110:113]
	v_mfma_f32_16x16x32_bf16 v[46:49], v[158:161], v[206:209], v[46:49]
	v_mfma_f32_16x16x32_bf16 v[46:49], v[162:165], v[210:213], v[46:49]
	v_mfma_f32_16x16x32_bf16 v[42:45], v[162:165], v[202:205], v[42:45]
	v_mfma_f32_16x16x32_bf16 v[42:45], v[158:161], v[198:201], v[42:45]
	v_mfma_f32_16x16x32_bf16 v[38:41], v[158:161], v[190:193], v[38:41]
	v_mfma_f32_16x16x32_bf16 v[38:41], v[162:165], v[194:197], v[38:41]
	v_mfma_f32_16x16x32_bf16 v[26:29], v[162:165], v[186:189], v[26:29]
	v_mfma_f32_16x16x32_bf16 v[26:29], v[158:161], v[182:185], v[26:29]
	v_mfma_f32_16x16x32_bf16 v[114:117], v[166:169], v[182:185], v[114:117]
	v_mfma_f32_16x16x32_bf16 v[114:117], v[170:173], v[186:189], v[114:117]
	v_mfma_f32_16x16x32_bf16 v[118:121], v[170:173], v[194:197], v[118:121]
	v_mfma_f32_16x16x32_bf16 v[118:121], v[166:169], v[190:193], v[118:121]
	v_mfma_f32_16x16x32_bf16 v[122:125], v[166:169], v[198:201], v[122:125]
	v_mfma_f32_16x16x32_bf16 v[122:125], v[170:173], v[202:205], v[122:125]
	v_mfma_f32_16x16x32_bf16 v[126:129], v[170:173], v[210:213], v[126:129]
	v_mfma_f32_16x16x32_bf16 v[126:129], v[166:169], v[206:209], v[126:129]
	v_mfma_f32_16x16x32_bf16 v[62:65], v[174:177], v[206:209], v[62:65]
	v_mfma_f32_16x16x32_bf16 v[62:65], v[178:181], v[210:213], v[62:65]
	v_mfma_f32_16x16x32_bf16 v[58:61], v[178:181], v[202:205], v[58:61]
	v_mfma_f32_16x16x32_bf16 v[58:61], v[174:177], v[198:201], v[58:61]
	s_setprio 1
	s_barrier
	v_mfma_f32_16x16x32_bf16 v[54:57], v[174:177], v[190:193], v[54:57]
	v_mfma_f32_16x16x32_bf16 v[54:57], v[178:181], v[194:197], v[54:57]
	v_mfma_f32_16x16x32_bf16 v[50:53], v[178:181], v[186:189], v[50:53]
	v_mfma_f32_16x16x32_bf16 v[50:53], v[174:177], v[182:185], v[50:53]
	s_setprio 0
	s_add_i32 s78, 0, 0x18000
	s_add_i32 s79, 0, 0x1c000
	ds_read_b128 v[150:153], v248
	ds_read_b128 v[154:157], v248 offset:1024
	ds_read_b128 v[158:161], v248 offset:2048
	ds_read_b128 v[162:165], v248 offset:3072
	ds_read_b128 v[166:169], v249
	ds_read_b128 v[170:173], v249 offset:1024
	ds_read_b128 v[174:177], v249 offset:2048
	ds_read_b128 v[178:181], v249 offset:3072
	ds_read_b128 v[182:185], v149 offset:32768
	ds_read_b128 v[186:189], v149 offset:33792
	ds_read_b128 v[190:193], v149 offset:34816
	ds_read_b128 v[194:197], v149 offset:35840
	ds_read_b128 v[198:201], v149 offset:36864
	ds_read_b128 v[202:205], v149 offset:37888
	ds_read_b128 v[206:209], v149 offset:38912
	ds_read_b128 v[210:213], v149 offset:39936
	s_add_u32 s50, s54, 0x40000
	s_addc_u32 s51, s55, 0
	s_mov_b32 m0, s62
	s_nop 0
	global_load_lds_dwordx4 v226, s[50:51]
	s_mov_b32 m0, s63
	s_nop 0
	global_load_lds_dwordx4 v230, s[50:51]
	s_waitcnt vmcnt(8)
	s_waitcnt lgkmcnt(0)
	s_barrier
	v_mfma_f32_16x16x32_bf16 v[78:81], v[150:153], v[182:185], v[78:81]
	v_mfma_f32_16x16x32_bf16 v[78:81], v[154:157], v[186:189], v[78:81]
	v_mfma_f32_16x16x32_bf16 v[66:69], v[154:157], v[194:197], v[66:69]
	v_mfma_f32_16x16x32_bf16 v[66:69], v[150:153], v[190:193], v[66:69]
	v_mfma_f32_16x16x32_bf16 v[70:73], v[150:153], v[198:201], v[70:73]
	v_mfma_f32_16x16x32_bf16 v[70:73], v[154:157], v[202:205], v[70:73]
	v_mfma_f32_16x16x32_bf16 v[74:77], v[154:157], v[210:213], v[74:77]
	v_mfma_f32_16x16x32_bf16 v[74:77], v[150:153], v[206:209], v[74:77]
	v_mfma_f32_16x16x32_bf16 v[10:13], v[158:161], v[206:209], v[10:13]
	v_mfma_f32_16x16x32_bf16 v[10:13], v[162:165], v[210:213], v[10:13]
	v_mfma_f32_16x16x32_bf16 v[6:9], v[162:165], v[202:205], v[6:9]
	v_mfma_f32_16x16x32_bf16 v[6:9], v[158:161], v[198:201], v[6:9]
	v_mfma_f32_16x16x32_bf16 v[2:5], v[158:161], v[190:193], v[2:5]
	v_mfma_f32_16x16x32_bf16 v[2:5], v[162:165], v[194:197], v[2:5]
	v_mfma_f32_16x16x32_bf16 v[14:17], v[162:165], v[186:189], v[14:17]
	v_mfma_f32_16x16x32_bf16 v[14:17], v[158:161], v[182:185], v[14:17]
	v_mfma_f32_16x16x32_bf16 v[98:101], v[166:169], v[182:185], v[98:101]
	v_mfma_f32_16x16x32_bf16 v[98:101], v[170:173], v[186:189], v[98:101]
	v_mfma_f32_16x16x32_bf16 v[82:85], v[170:173], v[194:197], v[82:85]
	v_mfma_f32_16x16x32_bf16 v[82:85], v[166:169], v[190:193], v[82:85]
	v_mfma_f32_16x16x32_bf16 v[86:89], v[166:169], v[198:201], v[86:89]
	v_mfma_f32_16x16x32_bf16 v[86:89], v[170:173], v[202:205], v[86:89]
	v_mfma_f32_16x16x32_bf16 v[94:97], v[170:173], v[210:213], v[94:97]
	v_mfma_f32_16x16x32_bf16 v[94:97], v[166:169], v[206:209], v[94:97]
	v_mfma_f32_16x16x32_bf16 v[30:33], v[174:177], v[206:209], v[30:33]
	v_mfma_f32_16x16x32_bf16 v[30:33], v[178:181], v[210:213], v[30:33]
	v_mfma_f32_16x16x32_bf16 v[22:25], v[178:181], v[202:205], v[22:25]
	v_mfma_f32_16x16x32_bf16 v[22:25], v[174:177], v[198:201], v[22:25]
	s_setprio 1
	s_barrier
	v_mfma_f32_16x16x32_bf16 v[18:21], v[174:177], v[190:193], v[18:21]
	v_mfma_f32_16x16x32_bf16 v[18:21], v[178:181], v[194:197], v[18:21]
	v_mfma_f32_16x16x32_bf16 v[34:37], v[178:181], v[186:189], v[34:37]
	v_mfma_f32_16x16x32_bf16 v[34:37], v[174:177], v[182:185], v[34:37]
	s_setprio 0
	ds_read_b128 v[182:185], v149 offset:49152
	ds_read_b128 v[186:189], v149 offset:50176
	ds_read_b128 v[190:193], v149 offset:51200
	ds_read_b128 v[194:197], v149 offset:52224
	ds_read_b128 v[198:201], v149 offset:53248
	ds_read_b128 v[202:205], v149 offset:54272
	ds_read_b128 v[206:209], v149 offset:55296
	ds_read_b128 v[210:213], v149 offset:56320
	s_add_u32 s98, s52, 0x80
	s_addc_u32 s99, s53, 0
	s_add_u32 s100, s54, 0x80
	s_addc_u32 s101, s55, 0
	s_add_i32 s50, s78, s15
	s_mov_b32 m0, s50
	s_nop 0
	global_load_lds_dwordx4 v228, s[98:99]
	s_add_i32 m0, s50, 0x2000
	s_add_u32 s50, s52, 0x40080
	s_addc_u32 s51, s53, 0
	global_load_lds_dwordx4 v232, s[98:99]
	s_add_i32 s52, s79, s15
	s_mov_b32 m0, s52
	s_nop 0
	global_load_lds_dwordx4 v228, s[50:51]
	s_add_i32 m0, s52, 0x2000
	s_nop 0
	global_load_lds_dwordx4 v232, s[50:51]
	s_mov_b32 m0, s68
	s_nop 0
	global_load_lds_dwordx4 v226, s[100:101]
	s_mov_b32 m0, s69
	s_nop 0
	global_load_lds_dwordx4 v230, s[100:101]
	s_waitcnt vmcnt(8)
	s_waitcnt lgkmcnt(0)
	s_barrier
	v_mfma_f32_16x16x32_bf16 v[90:93], v[150:153], v[182:185], v[90:93]
	v_mfma_f32_16x16x32_bf16 v[90:93], v[154:157], v[186:189], v[90:93]
	v_mfma_f32_16x16x32_bf16 v[102:105], v[154:157], v[194:197], v[102:105]
	v_mfma_f32_16x16x32_bf16 v[102:105], v[150:153], v[190:193], v[102:105]
	v_mfma_f32_16x16x32_bf16 v[106:109], v[150:153], v[198:201], v[106:109]
	v_mfma_f32_16x16x32_bf16 v[106:109], v[154:157], v[202:205], v[106:109]
	v_mfma_f32_16x16x32_bf16 v[110:113], v[154:157], v[210:213], v[110:113]
	v_mfma_f32_16x16x32_bf16 v[110:113], v[150:153], v[206:209], v[110:113]
	v_mfma_f32_16x16x32_bf16 v[46:49], v[158:161], v[206:209], v[46:49]
	v_mfma_f32_16x16x32_bf16 v[46:49], v[162:165], v[210:213], v[46:49]
	v_mfma_f32_16x16x32_bf16 v[42:45], v[162:165], v[202:205], v[42:45]
	v_mfma_f32_16x16x32_bf16 v[42:45], v[158:161], v[198:201], v[42:45]
	v_mfma_f32_16x16x32_bf16 v[38:41], v[158:161], v[190:193], v[38:41]
	v_mfma_f32_16x16x32_bf16 v[38:41], v[162:165], v[194:197], v[38:41]
	v_mfma_f32_16x16x32_bf16 v[26:29], v[162:165], v[186:189], v[26:29]
	v_mfma_f32_16x16x32_bf16 v[26:29], v[158:161], v[182:185], v[26:29]
	v_mfma_f32_16x16x32_bf16 v[114:117], v[166:169], v[182:185], v[114:117]
	v_mfma_f32_16x16x32_bf16 v[114:117], v[170:173], v[186:189], v[114:117]
	v_mfma_f32_16x16x32_bf16 v[118:121], v[170:173], v[194:197], v[118:121]
	v_mfma_f32_16x16x32_bf16 v[118:121], v[166:169], v[190:193], v[118:121]
	v_mfma_f32_16x16x32_bf16 v[122:125], v[166:169], v[198:201], v[122:125]
	v_mfma_f32_16x16x32_bf16 v[122:125], v[170:173], v[202:205], v[122:125]
	v_mfma_f32_16x16x32_bf16 v[126:129], v[170:173], v[210:213], v[126:129]
	v_mfma_f32_16x16x32_bf16 v[126:129], v[166:169], v[206:209], v[126:129]
	v_mfma_f32_16x16x32_bf16 v[62:65], v[174:177], v[206:209], v[62:65]
	v_mfma_f32_16x16x32_bf16 v[62:65], v[178:181], v[210:213], v[62:65]
	v_mfma_f32_16x16x32_bf16 v[58:61], v[178:181], v[202:205], v[58:61]
	v_mfma_f32_16x16x32_bf16 v[58:61], v[174:177], v[198:201], v[58:61]
	s_setprio 1
	s_barrier
	v_mfma_f32_16x16x32_bf16 v[54:57], v[174:177], v[190:193], v[54:57]
	v_mfma_f32_16x16x32_bf16 v[54:57], v[178:181], v[194:197], v[54:57]
	v_mfma_f32_16x16x32_bf16 v[50:53], v[178:181], v[186:189], v[50:53]
	v_mfma_f32_16x16x32_bf16 v[50:53], v[174:177], v[182:185], v[50:53]
	s_setprio 0
	s_add_u32 s34, s34, 0x100
	s_addc_u32 s35, s35, 0
	s_add_u32 s21, s21, 0x100
	s_addc_u32 s23, s23, 0
	s_cmp_ge_i32 s77, s66
	s_mov_b32 s52, s77
	s_cbranch_scc0 .LBB0_872

.LBB0_1009:
	v_add_u32_e32 v0, s64, v187
	ds_read_b128 v[130:133], v0
	ds_read_b128 v[134:137], v0 offset:1024
	ds_read_b128 v[138:141], v0 offset:2048
	ds_read_b128 v[142:145], v0 offset:3072
	v_add_u32_e32 v0, s65, v187
	ds_read_b128 v[146:149], v0
	ds_read_b128 v[150:153], v0 offset:1024
	ds_read_b128 v[178:181], v0 offset:2048
	ds_read_b128 v[182:185], v0 offset:3072
	s_add_i32 s35, s42, 2
	s_add_u32 s43, s36, 0x3fc000
	s_addc_u32 s44, s37, 0
	s_cmp_eq_u32 s61, s42
	s_cselect_b32 s46, s28, s43
	s_cselect_b32 s47, s29, s44
	s_cselect_b32 s44, s30, s11
	s_cselect_b32 s45, s31, s27
	s_add_u32 s42, s46, 0x400000
	s_addc_u32 s43, s47, 0
	s_add_i32 m0, s51, 0xc000
	ds_read_b128 v[220:223], v215
	ds_read_b128 v[224:227], v215 offset:1024
	ds_read_b128 v[228:231], v215 offset:2048
	ds_read_b128 v[232:235], v215 offset:3072
	ds_read_b128 v[236:239], v215 offset:4096
	ds_read_b128 v[240:243], v215 offset:5120
	ds_read_b128 v[244:247], v215 offset:6144
	ds_read_b128 v[248:251], v215 offset:7168
	global_load_lds_dwordx4 v168, s[36:37]
	s_add_i32 m0, s51, 0xe000
	s_nop 0
	global_load_lds_dwordx4 v170, s[36:37]
	s_waitcnt vmcnt(8)
	s_waitcnt lgkmcnt(0)
	s_barrier
	v_mfma_f32_16x16x32_bf16 v[114:117], v[130:133], v[220:223], v[114:117]
	v_mfma_f32_16x16x32_bf16 v[114:117], v[134:137], v[224:227], v[114:117]
	v_mfma_f32_16x16x32_bf16 v[110:113], v[134:137], v[232:235], v[110:113]
	v_mfma_f32_16x16x32_bf16 v[110:113], v[130:133], v[228:231], v[110:113]
	v_mfma_f32_16x16x32_bf16 v[94:97], v[130:133], v[236:239], v[94:97]
	v_mfma_f32_16x16x32_bf16 v[94:97], v[134:137], v[240:243], v[94:97]
	v_mfma_f32_16x16x32_bf16 v[78:81], v[134:137], v[248:251], v[78:81]
	v_mfma_f32_16x16x32_bf16 v[78:81], v[130:133], v[244:247], v[78:81]
	v_mfma_f32_16x16x32_bf16 v[70:73], v[138:141], v[244:247], v[70:73]
	v_mfma_f32_16x16x32_bf16 v[70:73], v[142:145], v[248:251], v[70:73]
	v_mfma_f32_16x16x32_bf16 v[86:89], v[142:145], v[240:243], v[86:89]
	v_mfma_f32_16x16x32_bf16 v[86:89], v[138:141], v[236:239], v[86:89]
	v_mfma_f32_16x16x32_bf16 v[102:105], v[138:141], v[228:231], v[102:105]
	v_mfma_f32_16x16x32_bf16 v[102:105], v[142:145], v[232:235], v[102:105]
	v_mfma_f32_16x16x32_bf16 v[118:121], v[142:145], v[224:227], v[118:121]
	v_mfma_f32_16x16x32_bf16 v[118:121], v[138:141], v[220:223], v[118:121]
	v_mfma_f32_16x16x32_bf16 v[126:129], v[146:149], v[220:223], v[126:129]
	v_mfma_f32_16x16x32_bf16 v[126:129], v[150:153], v[224:227], v[126:129]
	v_mfma_f32_16x16x32_bf16 v[106:109], v[150:153], v[232:235], v[106:109]
	v_mfma_f32_16x16x32_bf16 v[106:109], v[146:149], v[228:231], v[106:109]
	v_mfma_f32_16x16x32_bf16 v[90:93], v[146:149], v[236:239], v[90:93]
	v_mfma_f32_16x16x32_bf16 v[90:93], v[150:153], v[240:243], v[90:93]
	v_mfma_f32_16x16x32_bf16 v[74:77], v[150:153], v[248:251], v[74:77]
	v_mfma_f32_16x16x32_bf16 v[74:77], v[146:149], v[244:247], v[74:77]
	v_mfma_f32_16x16x32_bf16 v[66:69], v[178:181], v[244:247], v[66:69]
	v_mfma_f32_16x16x32_bf16 v[66:69], v[182:185], v[248:251], v[66:69]
	v_mfma_f32_16x16x32_bf16 v[82:85], v[182:185], v[240:243], v[82:85]
	v_mfma_f32_16x16x32_bf16 v[82:85], v[178:181], v[236:239], v[82:85]
	s_setprio 1
	s_barrier
	v_mfma_f32_16x16x32_bf16 v[98:101], v[178:181], v[228:231], v[98:101]
	v_mfma_f32_16x16x32_bf16 v[98:101], v[182:185], v[232:235], v[98:101]
	v_mfma_f32_16x16x32_bf16 v[122:125], v[182:185], v[224:227], v[122:125]
	v_mfma_f32_16x16x32_bf16 v[122:125], v[178:181], v[220:223], v[122:125]
	s_setprio 0
	s_add_i32 s69, s64, s49
	s_mov_b32 m0, s69
	ds_read_b128 v[220:223], v215 offset:16384
	ds_read_b128 v[224:227], v215 offset:17408
	ds_read_b128 v[228:231], v215 offset:18432
	ds_read_b128 v[232:235], v215 offset:19456
	ds_read_b128 v[236:239], v215 offset:20480
	ds_read_b128 v[240:243], v215 offset:21504
	ds_read_b128 v[244:247], v215 offset:22528
	ds_read_b128 v[248:251], v215 offset:23552
	global_load_lds_dwordx4 v156, s[44:45]
	s_add_i32 m0, s69, 0x2000
	s_add_u32 s70, s44, 0xb0000
	v_lshl_add_u64 v[172:173], s[44:45], 0, v[160:161]
	s_addc_u32 s71, s45, 0
	s_add_i32 s69, s65, s49
	global_load_lds_dwordx4 v160, s[44:45]
	s_mov_b32 m0, s69
	s_nop 0
	global_load_lds_dwordx4 v156, s[70:71]
	s_add_i32 m0, s69, 0x2000
	s_nop 0
	global_load_lds_dwordx4 v160, s[70:71]
	s_mov_b32 m0, s51
	s_nop 0
	global_load_lds_dwordx4 v154, s[46:47]
	s_mov_b32 m0, s52
	s_nop 0
	global_load_lds_dwordx4 v158, s[46:47]
	s_waitcnt vmcnt(8)
	s_waitcnt lgkmcnt(0)
	s_barrier
	v_mfma_f32_16x16x32_bf16 v[50:53], v[130:133], v[220:223], v[50:53]
	v_mfma_f32_16x16x32_bf16 v[50:53], v[134:137], v[224:227], v[50:53]
	v_mfma_f32_16x16x32_bf16 v[54:57], v[142:145], v[224:227], v[54:57]
	v_mfma_f32_16x16x32_bf16 v[54:57], v[138:141], v[220:223], v[54:57]
	v_mfma_f32_16x16x32_bf16 v[46:49], v[130:133], v[228:231], v[46:49]
	v_mfma_f32_16x16x32_bf16 v[46:49], v[134:137], v[232:235], v[46:49]
	v_mfma_f32_16x16x32_bf16 v[38:41], v[142:145], v[232:235], v[38:41]
	v_mfma_f32_16x16x32_bf16 v[38:41], v[138:141], v[228:231], v[38:41]
	v_mfma_f32_16x16x32_bf16 v[30:33], v[130:133], v[236:239], v[30:33]
	v_mfma_f32_16x16x32_bf16 v[30:33], v[134:137], v[240:243], v[30:33]
	v_mfma_f32_16x16x32_bf16 v[22:25], v[142:145], v[240:243], v[22:25]
	v_mfma_f32_16x16x32_bf16 v[22:25], v[138:141], v[236:239], v[22:25]
	v_mfma_f32_16x16x32_bf16 v[14:17], v[130:133], v[244:247], v[14:17]
	v_mfma_f32_16x16x32_bf16 v[14:17], v[134:137], v[248:251], v[14:17]
	v_mfma_f32_16x16x32_bf16 v[62:65], v[150:153], v[224:227], v[62:65]
	v_mfma_f32_16x16x32_bf16 v[62:65], v[146:149], v[220:223], v[62:65]
	v_mfma_f32_16x16x32_bf16 v[58:61], v[178:181], v[220:223], v[58:61]
	v_mfma_f32_16x16x32_bf16 v[58:61], v[182:185], v[224:227], v[58:61]
	v_mfma_f32_16x16x32_bf16 v[42:45], v[150:153], v[232:235], v[42:45]
	v_mfma_f32_16x16x32_bf16 v[42:45], v[146:149], v[228:231], v[42:45]
	v_mfma_f32_16x16x32_bf16 v[34:37], v[178:181], v[228:231], v[34:37]
	v_mfma_f32_16x16x32_bf16 v[34:37], v[182:185], v[232:235], v[34:37]
	v_mfma_f32_16x16x32_bf16 v[26:29], v[150:153], v[240:243], v[26:29]
	v_mfma_f32_16x16x32_bf16 v[26:29], v[146:149], v[236:239], v[26:29]
	v_mfma_f32_16x16x32_bf16 v[18:21], v[178:181], v[236:239], v[18:21]
	v_mfma_f32_16x16x32_bf16 v[18:21], v[182:185], v[240:243], v[18:21]
	v_mfma_f32_16x16x32_bf16 v[10:13], v[150:153], v[248:251], v[10:13]
	v_mfma_f32_16x16x32_bf16 v[10:13], v[146:149], v[244:247], v[10:13]
	s_setprio 1
	s_barrier
	v_mfma_f32_16x16x32_bf16 v[6:9], v[138:141], v[244:247], v[6:9]
	v_mfma_f32_16x16x32_bf16 v[6:9], v[142:145], v[248:251], v[6:9]
	v_mfma_f32_16x16x32_bf16 v[0:3], v[178:181], v[244:247], v[2:5]
	v_mfma_f32_16x16x32_bf16 v[0:3], v[182:185], v[248:251], v[0:3]
	s_setprio 0
	s_add_i32 s69, 0, 0x18000
	v_add_u32_e32 v4, s69, v187
	s_add_i32 s70, 0, 0x1c000
	ds_read_b128 v[130:133], v4
	ds_read_b128 v[134:137], v4 offset:1024
	ds_read_b128 v[138:141], v4 offset:2048
	ds_read_b128 v[142:145], v4 offset:3072
	v_add_u32_e32 v4, s70, v187
	ds_read_b128 v[146:149], v4
	ds_read_b128 v[150:153], v4 offset:1024
	ds_read_b128 v[178:181], v4 offset:2048
	ds_read_b128 v[182:185], v4 offset:3072
	s_add_u32 s46, s46, 0x4000
	s_addc_u32 s47, s47, 0
	s_mov_b32 m0, s53
	ds_read_b128 v[220:223], v215 offset:32768
	ds_read_b128 v[224:227], v215 offset:33792
	ds_read_b128 v[228:231], v215 offset:34816
	ds_read_b128 v[232:235], v215 offset:35840
	ds_read_b128 v[236:239], v215 offset:36864
	ds_read_b128 v[240:243], v215 offset:37888
	ds_read_b128 v[244:247], v215 offset:38912
	ds_read_b128 v[248:251], v215 offset:39936
	global_load_lds_dwordx4 v154, s[46:47]
	s_mov_b32 m0, s54
	s_nop 0
	global_load_lds_dwordx4 v158, s[46:47]
	s_waitcnt vmcnt(8)
	s_waitcnt lgkmcnt(0)
	s_barrier
	v_mfma_f32_16x16x32_bf16 v[114:117], v[130:133], v[220:223], v[114:117]
	v_mfma_f32_16x16x32_bf16 v[114:117], v[134:137], v[224:227], v[114:117]
	v_mfma_f32_16x16x32_bf16 v[110:113], v[134:137], v[232:235], v[110:113]
	v_mfma_f32_16x16x32_bf16 v[110:113], v[130:133], v[228:231], v[110:113]
	v_mfma_f32_16x16x32_bf16 v[94:97], v[130:133], v[236:239], v[94:97]
	v_mfma_f32_16x16x32_bf16 v[94:97], v[134:137], v[240:243], v[94:97]
	v_mfma_f32_16x16x32_bf16 v[78:81], v[134:137], v[248:251], v[78:81]
	v_mfma_f32_16x16x32_bf16 v[78:81], v[130:133], v[244:247], v[78:81]
	v_mfma_f32_16x16x32_bf16 v[70:73], v[138:141], v[244:247], v[70:73]
	v_mfma_f32_16x16x32_bf16 v[70:73], v[142:145], v[248:251], v[70:73]
	v_mfma_f32_16x16x32_bf16 v[86:89], v[142:145], v[240:243], v[86:89]
	v_mfma_f32_16x16x32_bf16 v[86:89], v[138:141], v[236:239], v[86:89]
	v_mfma_f32_16x16x32_bf16 v[102:105], v[138:141], v[228:231], v[102:105]
	v_mfma_f32_16x16x32_bf16 v[102:105], v[142:145], v[232:235], v[102:105]
	v_mfma_f32_16x16x32_bf16 v[118:121], v[142:145], v[224:227], v[118:121]
	v_mfma_f32_16x16x32_bf16 v[118:121], v[138:141], v[220:223], v[118:121]
	v_mfma_f32_16x16x32_bf16 v[126:129], v[146:149], v[220:223], v[126:129]
	v_mfma_f32_16x16x32_bf16 v[126:129], v[150:153], v[224:227], v[126:129]
	v_mfma_f32_16x16x32_bf16 v[106:109], v[150:153], v[232:235], v[106:109]
	v_mfma_f32_16x16x32_bf16 v[106:109], v[146:149], v[228:231], v[106:109]
	v_mfma_f32_16x16x32_bf16 v[90:93], v[146:149], v[236:239], v[90:93]
	v_mfma_f32_16x16x32_bf16 v[90:93], v[150:153], v[240:243], v[90:93]
	v_mfma_f32_16x16x32_bf16 v[74:77], v[150:153], v[248:251], v[74:77]
	v_mfma_f32_16x16x32_bf16 v[74:77], v[146:149], v[244:247], v[74:77]
	v_mfma_f32_16x16x32_bf16 v[66:69], v[178:181], v[244:247], v[66:69]
	v_mfma_f32_16x16x32_bf16 v[66:69], v[182:185], v[248:251], v[66:69]
	v_mfma_f32_16x16x32_bf16 v[82:85], v[182:185], v[240:243], v[82:85]
	v_mfma_f32_16x16x32_bf16 v[82:85], v[178:181], v[236:239], v[82:85]
	s_setprio 1
	s_barrier
	v_mfma_f32_16x16x32_bf16 v[98:101], v[178:181], v[228:231], v[98:101]
	v_mfma_f32_16x16x32_bf16 v[98:101], v[182:185], v[232:235], v[98:101]
	v_mfma_f32_16x16x32_bf16 v[122:125], v[182:185], v[224:227], v[122:125]
	v_mfma_f32_16x16x32_bf16 v[122:125], v[178:181], v[220:223], v[122:125]
	s_setprio 0
	s_add_i32 s46, s69, s49
	s_mov_b32 m0, s46
	ds_read_b128 v[220:223], v215 offset:49152
	ds_read_b128 v[224:227], v215 offset:50176
	ds_read_b128 v[228:231], v215 offset:51200
	ds_read_b128 v[232:235], v215 offset:52224
	ds_read_b128 v[236:239], v215 offset:53248
	ds_read_b128 v[240:243], v215 offset:54272
	ds_read_b128 v[244:247], v215 offset:55296
	ds_read_b128 v[248:251], v215 offset:56320
	s_add_u32 s98, s44, s18
	s_addc_u32 s99, s45, s19
	global_load_lds_dwordx4 v156, s[98:99]
	s_add_i32 m0, s46, 0x2000
	s_add_u32 s44, s44, 0xb0080
	v_lshl_add_u64 v[4:5], v[172:173], 0, s[18:19]
	s_addc_u32 s45, s45, 0
	s_add_i32 s46, s70, s49
	global_load_lds_dwordx4 v[4:5], off
	s_mov_b32 m0, s46
	s_nop 0
	global_load_lds_dwordx4 v156, s[44:45]
	s_add_i32 m0, s46, 0x2000
	s_nop 0
	global_load_lds_dwordx4 v160, s[44:45]
	s_mov_b32 m0, s59
	s_nop 0
	global_load_lds_dwordx4 v154, s[42:43]
	s_mov_b32 m0, s60
	s_nop 0
	global_load_lds_dwordx4 v158, s[42:43]
	s_waitcnt vmcnt(8)
	s_waitcnt lgkmcnt(0)
	s_barrier
	v_mfma_f32_16x16x32_bf16 v[50:53], v[130:133], v[220:223], v[50:53]
	v_mfma_f32_16x16x32_bf16 v[50:53], v[134:137], v[224:227], v[50:53]
	v_mfma_f32_16x16x32_bf16 v[54:57], v[142:145], v[224:227], v[54:57]
	v_mfma_f32_16x16x32_bf16 v[54:57], v[138:141], v[220:223], v[54:57]
	v_mfma_f32_16x16x32_bf16 v[46:49], v[130:133], v[228:231], v[46:49]
	v_mfma_f32_16x16x32_bf16 v[46:49], v[134:137], v[232:235], v[46:49]
	v_mfma_f32_16x16x32_bf16 v[38:41], v[142:145], v[232:235], v[38:41]
	v_mfma_f32_16x16x32_bf16 v[38:41], v[138:141], v[228:231], v[38:41]
	v_mfma_f32_16x16x32_bf16 v[30:33], v[130:133], v[236:239], v[30:33]
	v_mfma_f32_16x16x32_bf16 v[30:33], v[134:137], v[240:243], v[30:33]
	v_mfma_f32_16x16x32_bf16 v[22:25], v[142:145], v[240:243], v[22:25]
	v_mfma_f32_16x16x32_bf16 v[22:25], v[138:141], v[236:239], v[22:25]
	v_mfma_f32_16x16x32_bf16 v[14:17], v[130:133], v[244:247], v[14:17]
	v_mfma_f32_16x16x32_bf16 v[14:17], v[134:137], v[248:251], v[14:17]
	v_mfma_f32_16x16x32_bf16 v[62:65], v[150:153], v[224:227], v[62:65]
	v_mfma_f32_16x16x32_bf16 v[62:65], v[146:149], v[220:223], v[62:65]
	v_mfma_f32_16x16x32_bf16 v[58:61], v[178:181], v[220:223], v[58:61]
	v_mfma_f32_16x16x32_bf16 v[58:61], v[182:185], v[224:227], v[58:61]
	v_mfma_f32_16x16x32_bf16 v[42:45], v[150:153], v[232:235], v[42:45]
	v_mfma_f32_16x16x32_bf16 v[42:45], v[146:149], v[228:231], v[42:45]
	v_mfma_f32_16x16x32_bf16 v[34:37], v[178:181], v[228:231], v[34:37]
	v_mfma_f32_16x16x32_bf16 v[34:37], v[182:185], v[232:235], v[34:37]
	v_mfma_f32_16x16x32_bf16 v[26:29], v[150:153], v[240:243], v[26:29]
	v_mfma_f32_16x16x32_bf16 v[26:29], v[146:149], v[236:239], v[26:29]
	v_mfma_f32_16x16x32_bf16 v[18:21], v[178:181], v[236:239], v[18:21]
	v_mfma_f32_16x16x32_bf16 v[18:21], v[182:185], v[240:243], v[18:21]
	v_mfma_f32_16x16x32_bf16 v[10:13], v[150:153], v[248:251], v[10:13]
	v_mfma_f32_16x16x32_bf16 v[10:13], v[146:149], v[244:247], v[10:13]
	s_setprio 1
	s_barrier
	v_mfma_f32_16x16x32_bf16 v[4:7], v[138:141], v[244:247], v[6:9]
	v_mfma_f32_16x16x32_bf16 v[6:9], v[142:145], v[248:251], v[4:7]
	v_mfma_f32_16x16x32_bf16 v[0:3], v[178:181], v[244:247], v[0:3]
	v_mfma_f32_16x16x32_bf16 v[2:5], v[182:185], v[248:251], v[0:3]
	s_setprio 0
	s_add_u32 s11, s11, 0x100
	s_addc_u32 s27, s27, 0
	s_add_u32 s36, s36, 0x800000
	s_addc_u32 s37, s37, 0
	s_cmp_ge_i32 s35, s58
	s_mov_b32 s42, s35
	s_cbranch_scc0 .LBB0_1009
	v_mov_b64_e32 v[234:235], v[174:175]
	s_and_b64 vcc, exec, s[22:23]
	s_cbranch_vccnz .LBB0_980
	s_branch .LBB0_981
